# MLA: rescale factor applied to the running row sum inside the rescale path (one VALU op fewer per tile) on top of the barrier placement
# baseline (speedup 1.0000x reference)
; __device__ __forceinline__ void finishSM9(f32x16& p0, f32x16& p1, float alpha, float& l_reg, v8i32& p8) {
; #pragma unroll
;   for (int r = 0; r < 16; ++r) { p0[r] = __builtin_amdgcn_exp2f(p0[r]); p1[r] = __builtin_amdgcn_exp2f(p1[r]); }
;   float ps = 0;
; #pragma unroll
;   for (int r = 0; r < 16; ++r) ps += p0[r];
; #pragma unroll
;   for (int r = 0; r < 16; ++r) ps += p1[r];
;   { auto rr = __builtin_amdgcn_permlane32_swap(__float_as_uint(ps), __float_as_uint(ps), false, false);
;     ps = __uint_as_float(rr[0]) + __uint_as_float(rr[1]); }
;   l_reg = l_reg * alpha + ps;
; #pragma unroll
;   for (int g = 0; g < 4; ++g) {
;     int w = __builtin_amdgcn_cvt_pk_fp8_f32(p0[4 * g], p0[4 * g + 1], 0, false); p8[g] = __builtin_amdgcn_cvt_pk_fp8_f32(p0[4 * g + 2], p0[4 * g + 3], w, true);
;     int u = __builtin_amdgcn_cvt_pk_fp8_f32(p1[4 * g], p1[4 * g + 1], 0, false); p8[4 + g] = __builtin_amdgcn_cvt_pk_fp8_f32(p1[4 * g + 2], p1[4 * g + 3], u, true); }
; }
; __device__ __forceinline__ void pv8(f32x16* o, const char* Vt, const v8i32 p8, int r32, int hi) {
;   const int sw = (r32 >> 2) & 3, a0 = r32 * 64 + (((hi * 2) ^ sw) << 4), a1 = r32 * 64 + (((hi * 2 + 1) ^ sw) << 4);
; #pragma unroll
;   for (int d0 = 0; d0 < 4; ++d0) {
;     const v8i32 vf = cat8(*reinterpret_cast<const v4i32*>(Vt + d0 * 2048 + a0), *reinterpret_cast<const v4i32*>(Vt + d0 * 2048 + a1));
;     o[d0] = __builtin_amdgcn_mfma_scale_f32_32x32x64_f8f6f4(p8, vf, o[d0], 0, 0, 0, 127, 0, 127); }
; }
; __device__ __forceinline__ void qkt9(f32x16& p0, f32x16& p1, const char* Kn, const char* Kr, const v8i32* qf, const float init, int r32, int hi) {
; #pragma unroll
;   for (int r = 0; r < 16; ++r) { p0[r] = init; p1[r] = init; }
; #pragma unroll
;   for (int s = 0; s < 2; ++s) { const int c0 = s * 4 + hi * 2;
;     const v8i32 a0 = cat8(*reinterpret_cast<const v4i32*>(Kn + KN8SW(r32, c0)), *reinterpret_cast<const v4i32*>(Kn + KN8SW(r32, c0 + 1)));
;     const v8i32 a1 = cat8(*reinterpret_cast<const v4i32*>(Kn + 4096 + KN8SW(r32, c0)), *reinterpret_cast<const v4i32*>(Kn + 4096 + KN8SW(r32, c0 + 1)));
;     p0 = __builtin_amdgcn_mfma_scale_f32_32x32x64_f8f6f4(a0, qf[s], p0, 0, 0, 0, 127, 0, 124);
;     p1 = __builtin_amdgcn_mfma_scale_f32_32x32x64_f8f6f4(a1, qf[s], p1, 0, 0, 0, 127, 0, 124); }
;   { const int c0 = hi * 2;
.LBB0_1321:
	ds_read_b128 v[114:117], v215 offset:24576
	ds_read_b128 v[118:121], v216 offset:24576
	ds_read_b128 v[222:225], v215 offset:28672
	ds_read_b128 v[226:229], v216 offset:28672
	global_load_dwordx4 v[158:161], v176, s[18:19]
	global_load_dwordx4 v[162:165], v178, s[16:17]
	global_load_dwordx4 v[154:157], v[180:181], off
	v_add_u32_e32 v176, 0x2000, v176
	v_add_u32_e32 v178, 0x20000, v178
	s_mov_b64 s[20:21], 0x1000
	v_lshl_add_u64 v[180:181], v[180:181], 0, s[20:21]
	v_exp_f32_e32 v0, v82
	v_exp_f32_e32 v177, v83
	v_exp_f32_e32 v179, v84
	v_exp_f32_e32 v254, v85
	v_add_f32_e32 v219, v0, v177
	v_cvt_pk_fp8_f32 v246, v0, v177
	v_add_f32_e32 v219, v179, v219
	v_add_f32_e32 v219, v254, v219
	v_cvt_pk_fp8_f32 v246, v179, v254 op_sel:[0,0,1]
	s_waitcnt lgkmcnt(2)
	v_mfma_scale_f32_32x32x64_f8f6f4 v[114:129], v[114:121], v[146:153], v[230:245], v194, v193 op_sel_hi:[0,0,0]
	v_exp_f32_e32 v0, v86
	v_exp_f32_e32 v177, v87
	v_exp_f32_e32 v179, v88
	v_exp_f32_e32 v254, v89
	v_add_f32_e32 v219, v0, v219
	v_add_f32_e32 v219, v177, v219
	v_cvt_pk_fp8_f32 v247, v0, v177
	v_add_f32_e32 v219, v179, v219
	v_add_f32_e32 v219, v254, v219
	v_cvt_pk_fp8_f32 v247, v179, v254 op_sel:[0,0,1]
	ds_read_b128 v[82:85], v213 offset:24576
	ds_read_b128 v[86:89], v214 offset:24576
	s_waitcnt lgkmcnt(2)
	v_mfma_scale_f32_32x32x64_f8f6f4 v[98:113], v[222:229], v[146:153], v[230:245], v194, v193 op_sel_hi:[0,0,0]
	ds_read_b128 v[222:225], v213 offset:28672
	ds_read_b128 v[226:229], v214 offset:28672
	v_exp_f32_e32 v0, v90
	v_exp_f32_e32 v177, v91
	v_exp_f32_e32 v179, v92
	v_exp_f32_e32 v254, v93
	v_add_f32_e32 v219, v0, v219
	v_add_f32_e32 v219, v177, v219
	v_cvt_pk_fp8_f32 v248, v0, v177
	v_add_f32_e32 v219, v179, v219
	v_add_f32_e32 v219, v254, v219
	v_cvt_pk_fp8_f32 v248, v179, v254 op_sel:[0,0,1]
	v_exp_f32_e32 v0, v94
	v_exp_f32_e32 v177, v95
	v_exp_f32_e32 v179, v96
	v_exp_f32_e32 v254, v97
	v_add_f32_e32 v219, v0, v219
	v_add_f32_e32 v219, v177, v219
	v_cvt_pk_fp8_f32 v249, v0, v177
	v_add_f32_e32 v219, v179, v219
	v_add_f32_e32 v219, v254, v219
	v_cvt_pk_fp8_f32 v249, v179, v254 op_sel:[0,0,1]
	ds_read_b128 v[90:93], v185 offset:36864
	ds_read_b128 v[94:97], v186 offset:36864
	s_waitcnt lgkmcnt(4)
	v_mfma_scale_f32_32x32x64_f8f6f4 v[114:129], v[82:89], v[138:145], v[114:129], v194, v193 op_sel_hi:[0,0,0]
	v_exp_f32_e32 v0, v66
	v_exp_f32_e32 v177, v67
	v_exp_f32_e32 v179, v68
	v_exp_f32_e32 v254, v69
	v_add_f32_e32 v219, v0, v219
	v_add_f32_e32 v219, v177, v219
	v_cvt_pk_fp8_f32 v250, v0, v177
	v_add_f32_e32 v219, v179, v219
	v_add_f32_e32 v219, v254, v219
	v_cvt_pk_fp8_f32 v250, v179, v254 op_sel:[0,0,1]
	s_waitcnt lgkmcnt(2)
	v_mfma_scale_f32_32x32x64_f8f6f4 v[98:113], v[222:229], v[138:145], v[98:113], v194, v193 op_sel_hi:[0,0,0]
	ds_read_b128 v[222:225], v185 offset:38912
	ds_read_b128 v[226:229], v186 offset:38912
	v_exp_f32_e32 v0, v70
	v_exp_f32_e32 v177, v71
	v_exp_f32_e32 v179, v72
	v_exp_f32_e32 v254, v73
	v_add_f32_e32 v219, v0, v219
	v_add_f32_e32 v219, v177, v219
	v_cvt_pk_fp8_f32 v251, v0, v177
	v_add_f32_e32 v219, v179, v219
	v_add_f32_e32 v219, v254, v219
	v_cvt_pk_fp8_f32 v251, v179, v254 op_sel:[0,0,1]
	v_exp_f32_e32 v0, v74
	v_exp_f32_e32 v177, v75
	v_exp_f32_e32 v179, v76
	v_exp_f32_e32 v254, v77
	v_add_f32_e32 v219, v0, v219
	v_add_f32_e32 v219, v177, v219
	v_cvt_pk_fp8_f32 v252, v0, v177
	v_add_f32_e32 v219, v179, v219
	v_add_f32_e32 v219, v254, v219
	v_cvt_pk_fp8_f32 v252, v179, v254 op_sel:[0,0,1]
	s_waitcnt lgkmcnt(2)
	v_mfma_scale_f32_32x32x64_f8f6f4 v[114:129], v[90:97], v[130:137], v[114:129], v194, v193 op_sel_hi:[0,0,0]
	v_exp_f32_e32 v0, v78
	v_exp_f32_e32 v177, v79
	v_exp_f32_e32 v179, v80
	v_exp_f32_e32 v254, v81
	v_add_f32_e32 v219, v0, v219
	v_add_f32_e32 v219, v177, v219
	v_cvt_pk_fp8_f32 v253, v0, v177
	v_add_f32_e32 v219, v179, v219
	v_add_f32_e32 v219, v254, v219
	v_cvt_pk_fp8_f32 v253, v179, v254 op_sel:[0,0,1]
	ds_read_b128 v[90:93], v185 offset:0
	ds_read_b128 v[94:97], v186 offset:0
	ds_read_b128 v[82:85], v185 offset:2048
	ds_read_b128 v[86:89], v186 offset:2048
	ds_read_b128 v[74:77], v185 offset:4096
	ds_read_b128 v[78:81], v186 offset:4096
	ds_read_b128 v[66:69], v185 offset:6144
	ds_read_b128 v[70:73], v186 offset:6144
	s_waitcnt lgkmcnt(8)
	v_mfma_scale_f32_32x32x64_f8f6f4 v[98:113], v[222:229], v[130:137], v[98:113], v194, v193 op_sel_hi:[0,0,0]
	v_mov_b32_e32 v0, v219
	s_nop 1
	v_permlane32_swap_b32_e32 v219, v0
	v_add_f32_e32 v219, v219, v0
	v_add_f32_e32 v209, v209, v219
	v_max_f32_e32 v177, v114, v115
	v_max3_f32 v177, v177, v116, v117
	v_max3_f32 v177, v177, v118, v119
	v_max3_f32 v177, v177, v120, v121
	v_max3_f32 v177, v177, v122, v123
	v_max3_f32 v177, v177, v124, v125
	v_max3_f32 v177, v177, v126, v127
	v_max3_f32 v177, v177, v128, v129
	s_waitcnt lgkmcnt(6)
	v_mfma_scale_f32_32x32x64_f8f6f4 v[50:65], v[246:253], v[90:97], v[50:65], v194, v194 op_sel_hi:[0,0,0]
	s_waitcnt lgkmcnt(4)
	v_mfma_scale_f32_32x32x64_f8f6f4 v[34:49], v[246:253], v[82:89], v[34:49], v194, v194 op_sel_hi:[0,0,0]
	s_waitcnt lgkmcnt(2)
	v_mfma_scale_f32_32x32x64_f8f6f4 v[18:33], v[246:253], v[74:81], v[18:33], v194, v194 op_sel_hi:[0,0,0]
	s_waitcnt vmcnt(0)
	ds_write_b128 v210, v[158:161] offset:43008
	ds_write_b128 v211, v[162:165] offset:51200
	ds_write_b128 v212, v[154:157] offset:59392
	s_waitcnt lgkmcnt(3)
	v_mfma_scale_f32_32x32x64_f8f6f4 v[2:17], v[246:253], v[66:73], v[2:17], v194, v194 op_sel_hi:[0,0,0]
	s_waitcnt lgkmcnt(0)
	s_barrier
	v_max_f32_e32 v0, v98, v99
	v_max3_f32 v0, v0, v100, v101
	v_max3_f32 v0, v0, v102, v103
	v_max3_f32 v0, v0, v104, v105
	v_max3_f32 v0, v0, v106, v107
	v_max3_f32 v0, v0, v108, v109
	v_max3_f32 v0, v0, v110, v111
	v_max3_f32 v0, v0, v112, v113
	v_max_f32_e32 v177, v177, v0
	v_mov_b32_e32 v0, v177
	s_nop 1
	v_permlane32_swap_b32_e32 v177, v0
	v_max_f32_e32 v177, v177, v0
	v_cmp_ge_f32_e32 vcc, s90, v177
	s_cmp_eq_u64 vcc, exec
	s_cbranch_scc0 .Lmla_h0_newmax
; __device__ __forceinline__ void finishSM9(f32x16& p0, f32x16& p1, float alpha, float& l_reg, v8i32& p8) {
; #pragma unroll
;   for (int r = 0; r < 16; ++r) { p0[r] = __builtin_amdgcn_exp2f(p0[r]); p1[r] = __builtin_amdgcn_exp2f(p1[r]); }
;   float ps = 0;
; #pragma unroll
;   for (int r = 0; r < 16; ++r) ps += p0[r];
; #pragma unroll
;   for (int r = 0; r < 16; ++r) ps += p1[r];
;   { auto rr = __builtin_amdgcn_permlane32_swap(__float_as_uint(ps), __float_as_uint(ps), false, false);
;     ps = __uint_as_float(rr[0]) + __uint_as_float(rr[1]); }
;   l_reg = l_reg * alpha + ps;
; #pragma unroll
;   for (int g = 0; g < 4; ++g) {
;     int w = __builtin_amdgcn_cvt_pk_fp8_f32(p0[4 * g], p0[4 * g + 1], 0, false); p8[g] = __builtin_amdgcn_cvt_pk_fp8_f32(p0[4 * g + 2], p0[4 * g + 3], w, true);
;     int u = __builtin_amdgcn_cvt_pk_fp8_f32(p1[4 * g], p1[4 * g + 1], 0, false); p8[4 + g] = __builtin_amdgcn_cvt_pk_fp8_f32(p1[4 * g + 2], p1[4 * g + 3], u, true); }
; }
; __device__ __forceinline__ void pv8(f32x16* o, const char* Vt, const v8i32 p8, int r32, int hi) {
;   const int sw = (r32 >> 2) & 3, a0 = r32 * 64 + (((hi * 2) ^ sw) << 4), a1 = r32 * 64 + (((hi * 2 + 1) ^ sw) << 4);
; #pragma unroll
;   for (int d0 = 0; d0 < 4; ++d0) {
;     const v8i32 vf = cat8(*reinterpret_cast<const v4i32*>(Vt + d0 * 2048 + a0), *reinterpret_cast<const v4i32*>(Vt + d0 * 2048 + a1));
;     o[d0] = __builtin_amdgcn_mfma_scale_f32_32x32x64_f8f6f4(p8, vf, o[d0], 0, 0, 0, 127, 0, 127); }
; }
; __device__ __forceinline__ void qkt9(f32x16& p0, f32x16& p1, const char* Kn, const char* Kr, const v8i32* qf, const float init, int r32, int hi) {
; #pragma unroll
;   for (int r = 0; r < 16; ++r) { p0[r] = init; p1[r] = init; }
; #pragma unroll
;   for (int s = 0; s < 2; ++s) { const int c0 = s * 4 + hi * 2;
;     const v8i32 a0 = cat8(*reinterpret_cast<const v4i32*>(Kn + KN8SW(r32, c0)), *reinterpret_cast<const v4i32*>(Kn + KN8SW(r32, c0 + 1)));
;     const v8i32 a1 = cat8(*reinterpret_cast<const v4i32*>(Kn + 4096 + KN8SW(r32, c0)), *reinterpret_cast<const v4i32*>(Kn + 4096 + KN8SW(r32, c0 + 1)));
;     p0 = __builtin_amdgcn_mfma_scale_f32_32x32x64_f8f6f4(a0, qf[s], p0, 0, 0, 0, 127, 0, 124);
;     p1 = __builtin_amdgcn_mfma_scale_f32_32x32x64_f8f6f4(a1, qf[s], p1, 0, 0, 0, 127, 0, 124); }
;   { const int c0 = hi * 2;
.Lmla_h0_cont:
	ds_read_b128 v[82:85], v215 offset:51200
	ds_read_b128 v[86:89], v216 offset:51200
	ds_read_b128 v[222:225], v215 offset:55296
	ds_read_b128 v[226:229], v216 offset:55296
	global_load_dwordx4 v[158:161], v176, s[18:19]
	global_load_dwordx4 v[162:165], v178, s[16:17]
	global_load_dwordx4 v[154:157], v[180:181], off
	v_add_u32_e32 v176, 0x2000, v176
	v_add_u32_e32 v178, 0x20000, v178
	s_mov_b64 s[20:21], 0x1000
	v_lshl_add_u64 v[180:181], v[180:181], 0, s[20:21]
	v_exp_f32_e32 v0, v114
	v_exp_f32_e32 v177, v115
	v_exp_f32_e32 v179, v116
	v_exp_f32_e32 v254, v117
	v_add_f32_e32 v219, v0, v177
	v_cvt_pk_fp8_f32 v246, v0, v177
	v_add_f32_e32 v219, v179, v219
	v_add_f32_e32 v219, v254, v219
	v_cvt_pk_fp8_f32 v246, v179, v254 op_sel:[0,0,1]
	s_waitcnt lgkmcnt(2)
	v_mfma_scale_f32_32x32x64_f8f6f4 v[82:97], v[82:89], v[146:153], v[230:245], v194, v193 op_sel_hi:[0,0,0]
	v_exp_f32_e32 v0, v118
	v_exp_f32_e32 v177, v119
	v_exp_f32_e32 v179, v120
	v_exp_f32_e32 v254, v121
	v_add_f32_e32 v219, v0, v219
	v_add_f32_e32 v219, v177, v219
	v_cvt_pk_fp8_f32 v247, v0, v177
	v_add_f32_e32 v219, v179, v219
	v_add_f32_e32 v219, v254, v219
	v_cvt_pk_fp8_f32 v247, v179, v254 op_sel:[0,0,1]
	ds_read_b128 v[114:117], v213 offset:51200
	ds_read_b128 v[118:121], v214 offset:51200
	s_waitcnt lgkmcnt(2)
	v_mfma_scale_f32_32x32x64_f8f6f4 v[66:81], v[222:229], v[146:153], v[230:245], v194, v193 op_sel_hi:[0,0,0]
	ds_read_b128 v[222:225], v213 offset:55296
	ds_read_b128 v[226:229], v214 offset:55296
	v_exp_f32_e32 v0, v122
	v_exp_f32_e32 v177, v123
	v_exp_f32_e32 v179, v124
	v_exp_f32_e32 v254, v125
	v_add_f32_e32 v219, v0, v219
	v_add_f32_e32 v219, v177, v219
	v_cvt_pk_fp8_f32 v248, v0, v177
	v_add_f32_e32 v219, v179, v219
	v_add_f32_e32 v219, v254, v219
	v_cvt_pk_fp8_f32 v248, v179, v254 op_sel:[0,0,1]
	v_exp_f32_e32 v0, v126
	v_exp_f32_e32 v177, v127
	v_exp_f32_e32 v179, v128
	v_exp_f32_e32 v254, v129
	v_add_f32_e32 v219, v0, v219
	v_add_f32_e32 v219, v177, v219
	v_cvt_pk_fp8_f32 v249, v0, v177
	v_add_f32_e32 v219, v179, v219
	v_add_f32_e32 v219, v254, v219
	v_cvt_pk_fp8_f32 v249, v179, v254 op_sel:[0,0,1]
	ds_read_b128 v[122:125], v185 offset:59392
	ds_read_b128 v[126:129], v186 offset:59392
	s_waitcnt lgkmcnt(4)
	v_mfma_scale_f32_32x32x64_f8f6f4 v[82:97], v[114:121], v[138:145], v[82:97], v194, v193 op_sel_hi:[0,0,0]
	v_exp_f32_e32 v0, v98
	v_exp_f32_e32 v177, v99
	v_exp_f32_e32 v179, v100
	v_exp_f32_e32 v254, v101
	v_add_f32_e32 v219, v0, v219
	v_add_f32_e32 v219, v177, v219
	v_cvt_pk_fp8_f32 v250, v0, v177
	v_add_f32_e32 v219, v179, v219
	v_add_f32_e32 v219, v254, v219
	v_cvt_pk_fp8_f32 v250, v179, v254 op_sel:[0,0,1]
	s_waitcnt lgkmcnt(2)
	v_mfma_scale_f32_32x32x64_f8f6f4 v[66:81], v[222:229], v[138:145], v[66:81], v194, v193 op_sel_hi:[0,0,0]
	ds_read_b128 v[222:225], v185 offset:61440
	ds_read_b128 v[226:229], v186 offset:61440
	v_exp_f32_e32 v0, v102
	v_exp_f32_e32 v177, v103
	v_exp_f32_e32 v179, v104
	v_exp_f32_e32 v254, v105
	v_add_f32_e32 v219, v0, v219
	v_add_f32_e32 v219, v177, v219
	v_cvt_pk_fp8_f32 v251, v0, v177
	v_add_f32_e32 v219, v179, v219
	v_add_f32_e32 v219, v254, v219
	v_cvt_pk_fp8_f32 v251, v179, v254 op_sel:[0,0,1]
	v_exp_f32_e32 v0, v106
	v_exp_f32_e32 v177, v107
	v_exp_f32_e32 v179, v108
	v_exp_f32_e32 v254, v109
	v_add_f32_e32 v219, v0, v219
	v_add_f32_e32 v219, v177, v219
	v_cvt_pk_fp8_f32 v252, v0, v177
	v_add_f32_e32 v219, v179, v219
	v_add_f32_e32 v219, v254, v219
	v_cvt_pk_fp8_f32 v252, v179, v254 op_sel:[0,0,1]
	s_waitcnt lgkmcnt(2)
	v_mfma_scale_f32_32x32x64_f8f6f4 v[82:97], v[122:129], v[130:137], v[82:97], v194, v193 op_sel_hi:[0,0,0]
	v_exp_f32_e32 v0, v110
	v_exp_f32_e32 v177, v111
	v_exp_f32_e32 v179, v112
	v_exp_f32_e32 v254, v113
	v_add_f32_e32 v219, v0, v219
	v_add_f32_e32 v219, v177, v219
	v_cvt_pk_fp8_f32 v253, v0, v177
	v_add_f32_e32 v219, v179, v219
	v_add_f32_e32 v219, v254, v219
	v_cvt_pk_fp8_f32 v253, v179, v254 op_sel:[0,0,1]
	ds_read_b128 v[122:125], v185 offset:8192
	ds_read_b128 v[126:129], v186 offset:8192
	ds_read_b128 v[114:117], v185 offset:10240
	ds_read_b128 v[118:121], v186 offset:10240
	ds_read_b128 v[106:109], v185 offset:12288
	ds_read_b128 v[110:113], v186 offset:12288
	ds_read_b128 v[98:101], v185 offset:14336
	ds_read_b128 v[102:105], v186 offset:14336
	s_waitcnt lgkmcnt(8)
	v_mfma_scale_f32_32x32x64_f8f6f4 v[66:81], v[222:229], v[130:137], v[66:81], v194, v193 op_sel_hi:[0,0,0]
	v_mov_b32_e32 v0, v219
	s_nop 1
	v_permlane32_swap_b32_e32 v219, v0
	v_add_f32_e32 v219, v219, v0
	v_add_f32_e32 v209, v209, v219
	v_max_f32_e32 v177, v82, v83
	v_max3_f32 v177, v177, v84, v85
	v_max3_f32 v177, v177, v86, v87
	v_max3_f32 v177, v177, v88, v89
	v_max3_f32 v177, v177, v90, v91
	v_max3_f32 v177, v177, v92, v93
	v_max3_f32 v177, v177, v94, v95
	v_max3_f32 v177, v177, v96, v97
	s_waitcnt lgkmcnt(6)
	v_mfma_scale_f32_32x32x64_f8f6f4 v[50:65], v[246:253], v[122:129], v[50:65], v194, v194 op_sel_hi:[0,0,0]
	s_waitcnt lgkmcnt(4)
	v_mfma_scale_f32_32x32x64_f8f6f4 v[34:49], v[246:253], v[114:121], v[34:49], v194, v194 op_sel_hi:[0,0,0]
	s_waitcnt lgkmcnt(2)
	v_mfma_scale_f32_32x32x64_f8f6f4 v[18:33], v[246:253], v[106:113], v[18:33], v194, v194 op_sel_hi:[0,0,0]
	s_waitcnt vmcnt(0)
	ds_write_b128 v210, v[158:161]
	ds_write_b128 v211, v[162:165] offset:16384
	ds_write_b128 v212, v[154:157] offset:32768
	s_waitcnt lgkmcnt(3)
	v_mfma_scale_f32_32x32x64_f8f6f4 v[2:17], v[246:253], v[98:105], v[2:17], v194, v194 op_sel_hi:[0,0,0]
	s_waitcnt lgkmcnt(0)
	s_barrier
	v_max_f32_e32 v0, v66, v67
	v_max3_f32 v0, v0, v68, v69
	v_max3_f32 v0, v0, v70, v71
	v_max3_f32 v0, v0, v72, v73
	v_max3_f32 v0, v0, v74, v75
	v_max3_f32 v0, v0, v76, v77
	v_max3_f32 v0, v0, v78, v79
	v_max3_f32 v0, v0, v80, v81
	v_max_f32_e32 v177, v177, v0
	v_mov_b32_e32 v0, v177
	s_nop 1
	v_permlane32_swap_b32_e32 v177, v0
	v_max_f32_e32 v177, v177, v0
	v_cmp_ge_f32_e32 vcc, s90, v177
	s_cmp_eq_u64 vcc, exec
	s_cbranch_scc0 .Lmla_h1_newmax
; __device__ __forceinline__ void finishSM9(f32x16& p0, f32x16& p1, float alpha, float& l_reg, v8i32& p8) {
; #pragma unroll
;   for (int r = 0; r < 16; ++r) { p0[r] = __builtin_amdgcn_exp2f(p0[r]); p1[r] = __builtin_amdgcn_exp2f(p1[r]); }
;   float ps = 0;
; #pragma unroll
;   for (int r = 0; r < 16; ++r) ps += p0[r];
; #pragma unroll
;   for (int r = 0; r < 16; ++r) ps += p1[r];
;   { auto rr = __builtin_amdgcn_permlane32_swap(__float_as_uint(ps), __float_as_uint(ps), false, false);
;     ps = __uint_as_float(rr[0]) + __uint_as_float(rr[1]); }
;   l_reg = l_reg * alpha + ps;
; #pragma unroll
;   for (int g = 0; g < 4; ++g) {
;     int w = __builtin_amdgcn_cvt_pk_fp8_f32(p0[4 * g], p0[4 * g + 1], 0, false); p8[g] = __builtin_amdgcn_cvt_pk_fp8_f32(p0[4 * g + 2], p0[4 * g + 3], w, true);
;     int u = __builtin_amdgcn_cvt_pk_fp8_f32(p1[4 * g], p1[4 * g + 1], 0, false); p8[4 + g] = __builtin_amdgcn_cvt_pk_fp8_f32(p1[4 * g + 2], p1[4 * g + 3], u, true); }
; }
; __device__ __forceinline__ void pv8(f32x16* o, const char* Vt, const v8i32 p8, int r32, int hi) {
;   const int sw = (r32 >> 2) & 3, a0 = r32 * 64 + (((hi * 2) ^ sw) << 4), a1 = r32 * 64 + (((hi * 2 + 1) ^ sw) << 4);
; #pragma unroll
;   for (int d0 = 0; d0 < 4; ++d0) {
;     const v8i32 vf = cat8(*reinterpret_cast<const v4i32*>(Vt + d0 * 2048 + a0), *reinterpret_cast<const v4i32*>(Vt + d0 * 2048 + a1));
;     o[d0] = __builtin_amdgcn_mfma_scale_f32_32x32x64_f8f6f4(p8, vf, o[d0], 0, 0, 0, 127, 0, 127); }
; }
; __device__ __forceinline__ void qkt9(f32x16& p0, f32x16& p1, const char* Kn, const char* Kr, const v8i32* qf, const float init, int r32, int hi) {
; #pragma unroll
;   for (int r = 0; r < 16; ++r) { p0[r] = init; p1[r] = init; }
; #pragma unroll
;   for (int s = 0; s < 2; ++s) { const int c0 = s * 4 + hi * 2;
;     const v8i32 a0 = cat8(*reinterpret_cast<const v4i32*>(Kn + KN8SW(r32, c0)), *reinterpret_cast<const v4i32*>(Kn + KN8SW(r32, c0 + 1)));
;     const v8i32 a1 = cat8(*reinterpret_cast<const v4i32*>(Kn + 4096 + KN8SW(r32, c0)), *reinterpret_cast<const v4i32*>(Kn + 4096 + KN8SW(r32, c0 + 1)));
;     p0 = __builtin_amdgcn_mfma_scale_f32_32x32x64_f8f6f4(a0, qf[s], p0, 0, 0, 0, 127, 0, 124);
;     p1 = __builtin_amdgcn_mfma_scale_f32_32x32x64_f8f6f4(a1, qf[s], p1, 0, 0, 0, 127, 0, 124); }
;   { const int c0 = hi * 2;
.Lmla_h1_cont:
	ds_read_b128 v[114:117], v215 offset:16384
	ds_read_b128 v[118:121], v216 offset:16384
	ds_read_b128 v[222:225], v215 offset:20480
	ds_read_b128 v[226:229], v216 offset:20480
	global_load_dwordx4 v[158:161], v176, s[18:19]
	global_load_dwordx4 v[162:165], v178, s[16:17]
	global_load_dwordx4 v[154:157], v[180:181], off
	v_add_u32_e32 v176, 0x2000, v176
	v_add_u32_e32 v178, 0x20000, v178
	s_mov_b64 s[20:21], 0x1000
	v_lshl_add_u64 v[180:181], v[180:181], 0, s[20:21]
	v_exp_f32_e32 v0, v82
	v_exp_f32_e32 v177, v83
	v_exp_f32_e32 v179, v84
	v_exp_f32_e32 v254, v85
	v_add_f32_e32 v219, v0, v177
	v_cvt_pk_fp8_f32 v246, v0, v177
	v_add_f32_e32 v219, v179, v219
	v_add_f32_e32 v219, v254, v219
	v_cvt_pk_fp8_f32 v246, v179, v254 op_sel:[0,0,1]
	s_waitcnt lgkmcnt(2)
	v_mfma_scale_f32_32x32x64_f8f6f4 v[114:129], v[114:121], v[146:153], v[230:245], v194, v193 op_sel_hi:[0,0,0]
	v_exp_f32_e32 v0, v86
	v_exp_f32_e32 v177, v87
	v_exp_f32_e32 v179, v88
	v_exp_f32_e32 v254, v89
	v_add_f32_e32 v219, v0, v219
	v_add_f32_e32 v219, v177, v219
	v_cvt_pk_fp8_f32 v247, v0, v177
	v_add_f32_e32 v219, v179, v219
	v_add_f32_e32 v219, v254, v219
	v_cvt_pk_fp8_f32 v247, v179, v254 op_sel:[0,0,1]
	ds_read_b128 v[82:85], v213 offset:16384
	ds_read_b128 v[86:89], v214 offset:16384
	s_waitcnt lgkmcnt(2)
	v_mfma_scale_f32_32x32x64_f8f6f4 v[98:113], v[222:229], v[146:153], v[230:245], v194, v193 op_sel_hi:[0,0,0]
	ds_read_b128 v[222:225], v213 offset:20480
	ds_read_b128 v[226:229], v214 offset:20480
	v_exp_f32_e32 v0, v90
	v_exp_f32_e32 v177, v91
	v_exp_f32_e32 v179, v92
	v_exp_f32_e32 v254, v93
	v_add_f32_e32 v219, v0, v219
	v_add_f32_e32 v219, v177, v219
	v_cvt_pk_fp8_f32 v248, v0, v177
	v_add_f32_e32 v219, v179, v219
	v_add_f32_e32 v219, v254, v219
	v_cvt_pk_fp8_f32 v248, v179, v254 op_sel:[0,0,1]
	v_exp_f32_e32 v0, v94
	v_exp_f32_e32 v177, v95
	v_exp_f32_e32 v179, v96
	v_exp_f32_e32 v254, v97
	v_add_f32_e32 v219, v0, v219
	v_add_f32_e32 v219, v177, v219
	v_cvt_pk_fp8_f32 v249, v0, v177
	v_add_f32_e32 v219, v179, v219
	v_add_f32_e32 v219, v254, v219
	v_cvt_pk_fp8_f32 v249, v179, v254 op_sel:[0,0,1]
	ds_read_b128 v[90:93], v185 offset:32768
	ds_read_b128 v[94:97], v186 offset:32768
	s_waitcnt lgkmcnt(4)
	v_mfma_scale_f32_32x32x64_f8f6f4 v[114:129], v[82:89], v[138:145], v[114:129], v194, v193 op_sel_hi:[0,0,0]
	v_exp_f32_e32 v0, v66
	v_exp_f32_e32 v177, v67
	v_exp_f32_e32 v179, v68
	v_exp_f32_e32 v254, v69
	v_add_f32_e32 v219, v0, v219
	v_add_f32_e32 v219, v177, v219
	v_cvt_pk_fp8_f32 v250, v0, v177
	v_add_f32_e32 v219, v179, v219
	v_add_f32_e32 v219, v254, v219
	v_cvt_pk_fp8_f32 v250, v179, v254 op_sel:[0,0,1]
	s_waitcnt lgkmcnt(2)
	v_mfma_scale_f32_32x32x64_f8f6f4 v[98:113], v[222:229], v[138:145], v[98:113], v194, v193 op_sel_hi:[0,0,0]
	ds_read_b128 v[222:225], v185 offset:34816
	ds_read_b128 v[226:229], v186 offset:34816
	v_exp_f32_e32 v0, v70
	v_exp_f32_e32 v177, v71
	v_exp_f32_e32 v179, v72
	v_exp_f32_e32 v254, v73
	v_add_f32_e32 v219, v0, v219
	v_add_f32_e32 v219, v177, v219
	v_cvt_pk_fp8_f32 v251, v0, v177
	v_add_f32_e32 v219, v179, v219
	v_add_f32_e32 v219, v254, v219
	v_cvt_pk_fp8_f32 v251, v179, v254 op_sel:[0,0,1]
	v_exp_f32_e32 v0, v74
	v_exp_f32_e32 v177, v75
	v_exp_f32_e32 v179, v76
	v_exp_f32_e32 v254, v77
	v_add_f32_e32 v219, v0, v219
	v_add_f32_e32 v219, v177, v219
	v_cvt_pk_fp8_f32 v252, v0, v177
	v_add_f32_e32 v219, v179, v219
	v_add_f32_e32 v219, v254, v219
	v_cvt_pk_fp8_f32 v252, v179, v254 op_sel:[0,0,1]
	s_waitcnt lgkmcnt(2)
	v_mfma_scale_f32_32x32x64_f8f6f4 v[114:129], v[90:97], v[130:137], v[114:129], v194, v193 op_sel_hi:[0,0,0]
	v_exp_f32_e32 v0, v78
	v_exp_f32_e32 v177, v79
	v_exp_f32_e32 v179, v80
	v_exp_f32_e32 v254, v81
	v_add_f32_e32 v219, v0, v219
	v_add_f32_e32 v219, v177, v219
	v_cvt_pk_fp8_f32 v253, v0, v177
	v_add_f32_e32 v219, v179, v219
	v_add_f32_e32 v219, v254, v219
	v_cvt_pk_fp8_f32 v253, v179, v254 op_sel:[0,0,1]
	ds_read_b128 v[90:93], v185 offset:43008
	ds_read_b128 v[94:97], v186 offset:43008
	ds_read_b128 v[82:85], v185 offset:45056
	ds_read_b128 v[86:89], v186 offset:45056
	ds_read_b128 v[74:77], v185 offset:47104
	ds_read_b128 v[78:81], v186 offset:47104
	ds_read_b128 v[66:69], v185 offset:49152
	ds_read_b128 v[70:73], v186 offset:49152
	s_waitcnt lgkmcnt(8)
	v_mfma_scale_f32_32x32x64_f8f6f4 v[98:113], v[222:229], v[130:137], v[98:113], v194, v193 op_sel_hi:[0,0,0]
	v_mov_b32_e32 v0, v219
	s_nop 1
	v_permlane32_swap_b32_e32 v219, v0
	v_add_f32_e32 v219, v219, v0
	v_add_f32_e32 v209, v209, v219
	v_max_f32_e32 v177, v114, v115
	v_max3_f32 v177, v177, v116, v117
	v_max3_f32 v177, v177, v118, v119
	v_max3_f32 v177, v177, v120, v121
	v_max3_f32 v177, v177, v122, v123
	v_max3_f32 v177, v177, v124, v125
	v_max3_f32 v177, v177, v126, v127
	v_max3_f32 v177, v177, v128, v129
	s_waitcnt lgkmcnt(6)
	v_mfma_scale_f32_32x32x64_f8f6f4 v[50:65], v[246:253], v[90:97], v[50:65], v194, v194 op_sel_hi:[0,0,0]
	s_waitcnt lgkmcnt(4)
	v_mfma_scale_f32_32x32x64_f8f6f4 v[34:49], v[246:253], v[82:89], v[34:49], v194, v194 op_sel_hi:[0,0,0]
	s_waitcnt lgkmcnt(2)
	v_mfma_scale_f32_32x32x64_f8f6f4 v[18:33], v[246:253], v[74:81], v[18:33], v194, v194 op_sel_hi:[0,0,0]
	s_waitcnt vmcnt(0)
	ds_write_b128 v210, v[158:161] offset:8192
	ds_write_b128 v211, v[162:165] offset:24576
	ds_write_b128 v212, v[154:157] offset:36864
	s_waitcnt lgkmcnt(3)
	v_mfma_scale_f32_32x32x64_f8f6f4 v[2:17], v[246:253], v[66:73], v[2:17], v194, v194 op_sel_hi:[0,0,0]
	s_waitcnt lgkmcnt(0)
	s_barrier
	v_max_f32_e32 v0, v98, v99
	v_max3_f32 v0, v0, v100, v101
	v_max3_f32 v0, v0, v102, v103
	v_max3_f32 v0, v0, v104, v105
	v_max3_f32 v0, v0, v106, v107
	v_max3_f32 v0, v0, v108, v109
	v_max3_f32 v0, v0, v110, v111
	v_max3_f32 v0, v0, v112, v113
	v_max_f32_e32 v177, v177, v0
	v_mov_b32_e32 v0, v177
	s_nop 1
	v_permlane32_swap_b32_e32 v177, v0
	v_max_f32_e32 v177, v177, v0
	v_cmp_ge_f32_e32 vcc, s90, v177
	s_cmp_eq_u64 vcc, exec
	s_cbranch_scc0 .Lmla_h2_newmax
; __device__ __forceinline__ void finishSM9(f32x16& p0, f32x16& p1, float alpha, float& l_reg, v8i32& p8) {
; #pragma unroll
;   for (int r = 0; r < 16; ++r) { p0[r] = __builtin_amdgcn_exp2f(p0[r]); p1[r] = __builtin_amdgcn_exp2f(p1[r]); }
;   float ps = 0;
; #pragma unroll
;   for (int r = 0; r < 16; ++r) ps += p0[r];
; #pragma unroll
;   for (int r = 0; r < 16; ++r) ps += p1[r];
;   { auto rr = __builtin_amdgcn_permlane32_swap(__float_as_uint(ps), __float_as_uint(ps), false, false);
;     ps = __uint_as_float(rr[0]) + __uint_as_float(rr[1]); }
;   l_reg = l_reg * alpha + ps;
; #pragma unroll
;   for (int g = 0; g < 4; ++g) {
;     int w = __builtin_amdgcn_cvt_pk_fp8_f32(p0[4 * g], p0[4 * g + 1], 0, false); p8[g] = __builtin_amdgcn_cvt_pk_fp8_f32(p0[4 * g + 2], p0[4 * g + 3], w, true);
;     int u = __builtin_amdgcn_cvt_pk_fp8_f32(p1[4 * g], p1[4 * g + 1], 0, false); p8[4 + g] = __builtin_amdgcn_cvt_pk_fp8_f32(p1[4 * g + 2], p1[4 * g + 3], u, true); }
; }
; __device__ __forceinline__ void pv8(f32x16* o, const char* Vt, const v8i32 p8, int r32, int hi) {
;   const int sw = (r32 >> 2) & 3, a0 = r32 * 64 + (((hi * 2) ^ sw) << 4), a1 = r32 * 64 + (((hi * 2 + 1) ^ sw) << 4);
; #pragma unroll
;   for (int d0 = 0; d0 < 4; ++d0) {
;     const v8i32 vf = cat8(*reinterpret_cast<const v4i32*>(Vt + d0 * 2048 + a0), *reinterpret_cast<const v4i32*>(Vt + d0 * 2048 + a1));
;     o[d0] = __builtin_amdgcn_mfma_scale_f32_32x32x64_f8f6f4(p8, vf, o[d0], 0, 0, 0, 127, 0, 127); }
; }
; __device__ __forceinline__ void qkt9(f32x16& p0, f32x16& p1, const char* Kn, const char* Kr, const v8i32* qf, const float init, int r32, int hi) {
; #pragma unroll
;   for (int r = 0; r < 16; ++r) { p0[r] = init; p1[r] = init; }
; #pragma unroll
;   for (int s = 0; s < 2; ++s) { const int c0 = s * 4 + hi * 2;
;     const v8i32 a0 = cat8(*reinterpret_cast<const v4i32*>(Kn + KN8SW(r32, c0)), *reinterpret_cast<const v4i32*>(Kn + KN8SW(r32, c0 + 1)));
;     const v8i32 a1 = cat8(*reinterpret_cast<const v4i32*>(Kn + 4096 + KN8SW(r32, c0)), *reinterpret_cast<const v4i32*>(Kn + 4096 + KN8SW(r32, c0 + 1)));
;     p0 = __builtin_amdgcn_mfma_scale_f32_32x32x64_f8f6f4(a0, qf[s], p0, 0, 0, 0, 127, 0, 124);
;     p1 = __builtin_amdgcn_mfma_scale_f32_32x32x64_f8f6f4(a1, qf[s], p1, 0, 0, 0, 127, 0, 124); }
;   { const int c0 = hi * 2;
.Lmla_h2_cont:
	ds_read_b128 v[82:85], v215 offset:24576
	ds_read_b128 v[86:89], v216 offset:24576
	ds_read_b128 v[222:225], v215 offset:28672
	ds_read_b128 v[226:229], v216 offset:28672
	global_load_dwordx4 v[158:161], v176, s[18:19]
	global_load_dwordx4 v[162:165], v178, s[16:17]
	global_load_dwordx4 v[154:157], v[180:181], off
	v_add_u32_e32 v176, 0x2000, v176
	v_add_u32_e32 v178, 0x20000, v178
	s_mov_b64 s[20:21], 0x1000
	v_lshl_add_u64 v[180:181], v[180:181], 0, s[20:21]
	v_exp_f32_e32 v0, v114
	v_exp_f32_e32 v177, v115
	v_exp_f32_e32 v179, v116
	v_exp_f32_e32 v254, v117
	v_add_f32_e32 v219, v0, v177
	v_cvt_pk_fp8_f32 v246, v0, v177
	v_add_f32_e32 v219, v179, v219
	v_add_f32_e32 v219, v254, v219
	v_cvt_pk_fp8_f32 v246, v179, v254 op_sel:[0,0,1]
	s_waitcnt lgkmcnt(2)
	v_mfma_scale_f32_32x32x64_f8f6f4 v[82:97], v[82:89], v[146:153], v[230:245], v194, v193 op_sel_hi:[0,0,0]
	v_exp_f32_e32 v0, v118
	v_exp_f32_e32 v177, v119
	v_exp_f32_e32 v179, v120
	v_exp_f32_e32 v254, v121
	v_add_f32_e32 v219, v0, v219
	v_add_f32_e32 v219, v177, v219
	v_cvt_pk_fp8_f32 v247, v0, v177
	v_add_f32_e32 v219, v179, v219
	v_add_f32_e32 v219, v254, v219
	v_cvt_pk_fp8_f32 v247, v179, v254 op_sel:[0,0,1]
	ds_read_b128 v[114:117], v213 offset:24576
	ds_read_b128 v[118:121], v214 offset:24576
	s_waitcnt lgkmcnt(2)
	v_mfma_scale_f32_32x32x64_f8f6f4 v[66:81], v[222:229], v[146:153], v[230:245], v194, v193 op_sel_hi:[0,0,0]
	ds_read_b128 v[222:225], v213 offset:28672
	ds_read_b128 v[226:229], v214 offset:28672
	v_exp_f32_e32 v0, v122
	v_exp_f32_e32 v177, v123
	v_exp_f32_e32 v179, v124
	v_exp_f32_e32 v254, v125
	v_add_f32_e32 v219, v0, v219
	v_add_f32_e32 v219, v177, v219
	v_cvt_pk_fp8_f32 v248, v0, v177
	v_add_f32_e32 v219, v179, v219
	v_add_f32_e32 v219, v254, v219
	v_cvt_pk_fp8_f32 v248, v179, v254 op_sel:[0,0,1]
	v_exp_f32_e32 v0, v126
	v_exp_f32_e32 v177, v127
	v_exp_f32_e32 v179, v128
	v_exp_f32_e32 v254, v129
	v_add_f32_e32 v219, v0, v219
	v_add_f32_e32 v219, v177, v219
	v_cvt_pk_fp8_f32 v249, v0, v177
	v_add_f32_e32 v219, v179, v219
	v_add_f32_e32 v219, v254, v219
	v_cvt_pk_fp8_f32 v249, v179, v254 op_sel:[0,0,1]
	ds_read_b128 v[122:125], v185 offset:36864
	ds_read_b128 v[126:129], v186 offset:36864
	s_waitcnt lgkmcnt(4)
	v_mfma_scale_f32_32x32x64_f8f6f4 v[82:97], v[114:121], v[138:145], v[82:97], v194, v193 op_sel_hi:[0,0,0]
	v_exp_f32_e32 v0, v98
	v_exp_f32_e32 v177, v99
	v_exp_f32_e32 v179, v100
	v_exp_f32_e32 v254, v101
	v_add_f32_e32 v219, v0, v219
	v_add_f32_e32 v219, v177, v219
	v_cvt_pk_fp8_f32 v250, v0, v177
	v_add_f32_e32 v219, v179, v219
	v_add_f32_e32 v219, v254, v219
	v_cvt_pk_fp8_f32 v250, v179, v254 op_sel:[0,0,1]
	s_waitcnt lgkmcnt(2)
	v_mfma_scale_f32_32x32x64_f8f6f4 v[66:81], v[222:229], v[138:145], v[66:81], v194, v193 op_sel_hi:[0,0,0]
	ds_read_b128 v[222:225], v185 offset:38912
	ds_read_b128 v[226:229], v186 offset:38912
	v_exp_f32_e32 v0, v102
	v_exp_f32_e32 v177, v103
	v_exp_f32_e32 v179, v104
	v_exp_f32_e32 v254, v105
	v_add_f32_e32 v219, v0, v219
	v_add_f32_e32 v219, v177, v219
	v_cvt_pk_fp8_f32 v251, v0, v177
	v_add_f32_e32 v219, v179, v219
	v_add_f32_e32 v219, v254, v219
	v_cvt_pk_fp8_f32 v251, v179, v254 op_sel:[0,0,1]
	v_exp_f32_e32 v0, v106
	v_exp_f32_e32 v177, v107
	v_exp_f32_e32 v179, v108
	v_exp_f32_e32 v254, v109
	v_add_f32_e32 v219, v0, v219
	v_add_f32_e32 v219, v177, v219
	v_cvt_pk_fp8_f32 v252, v0, v177
	v_add_f32_e32 v219, v179, v219
	v_add_f32_e32 v219, v254, v219
	v_cvt_pk_fp8_f32 v252, v179, v254 op_sel:[0,0,1]
	s_waitcnt lgkmcnt(2)
	v_mfma_scale_f32_32x32x64_f8f6f4 v[82:97], v[122:129], v[130:137], v[82:97], v194, v193 op_sel_hi:[0,0,0]
	v_exp_f32_e32 v0, v110
	v_exp_f32_e32 v177, v111
	v_exp_f32_e32 v179, v112
	v_exp_f32_e32 v254, v113
	v_add_f32_e32 v219, v0, v219
	v_add_f32_e32 v219, v177, v219
	v_cvt_pk_fp8_f32 v253, v0, v177
	v_add_f32_e32 v219, v179, v219
	v_add_f32_e32 v219, v254, v219
	v_cvt_pk_fp8_f32 v253, v179, v254 op_sel:[0,0,1]
	ds_read_b128 v[122:125], v185 offset:0
	ds_read_b128 v[126:129], v186 offset:0
	ds_read_b128 v[114:117], v185 offset:2048
	ds_read_b128 v[118:121], v186 offset:2048
	ds_read_b128 v[106:109], v185 offset:4096
	ds_read_b128 v[110:113], v186 offset:4096
	ds_read_b128 v[98:101], v185 offset:6144
	ds_read_b128 v[102:105], v186 offset:6144
	s_waitcnt lgkmcnt(8)
	v_mfma_scale_f32_32x32x64_f8f6f4 v[66:81], v[222:229], v[130:137], v[66:81], v194, v193 op_sel_hi:[0,0,0]
	v_mov_b32_e32 v0, v219
	s_nop 1
	v_permlane32_swap_b32_e32 v219, v0
	v_add_f32_e32 v219, v219, v0
	v_add_f32_e32 v209, v209, v219
	v_max_f32_e32 v177, v82, v83
	v_max3_f32 v177, v177, v84, v85
	v_max3_f32 v177, v177, v86, v87
	v_max3_f32 v177, v177, v88, v89
	v_max3_f32 v177, v177, v90, v91
	v_max3_f32 v177, v177, v92, v93
	v_max3_f32 v177, v177, v94, v95
	v_max3_f32 v177, v177, v96, v97
	s_waitcnt lgkmcnt(6)
	v_mfma_scale_f32_32x32x64_f8f6f4 v[50:65], v[246:253], v[122:129], v[50:65], v194, v194 op_sel_hi:[0,0,0]
	s_waitcnt lgkmcnt(4)
	v_mfma_scale_f32_32x32x64_f8f6f4 v[34:49], v[246:253], v[114:121], v[34:49], v194, v194 op_sel_hi:[0,0,0]
	s_waitcnt lgkmcnt(2)
	v_mfma_scale_f32_32x32x64_f8f6f4 v[18:33], v[246:253], v[106:113], v[18:33], v194, v194 op_sel_hi:[0,0,0]
	s_waitcnt vmcnt(0)
	ds_write_b128 v210, v[158:161] offset:43008
	ds_write_b128 v211, v[162:165] offset:51200
	ds_write_b128 v212, v[154:157] offset:59392
	s_waitcnt lgkmcnt(3)
	v_mfma_scale_f32_32x32x64_f8f6f4 v[2:17], v[246:253], v[98:105], v[2:17], v194, v194 op_sel_hi:[0,0,0]
	s_waitcnt lgkmcnt(0)
	s_barrier
	v_max_f32_e32 v0, v66, v67
	v_max3_f32 v0, v0, v68, v69
	v_max3_f32 v0, v0, v70, v71
	v_max3_f32 v0, v0, v72, v73
	v_max3_f32 v0, v0, v74, v75
	v_max3_f32 v0, v0, v76, v77
	v_max3_f32 v0, v0, v78, v79
	v_max3_f32 v0, v0, v80, v81
	v_max_f32_e32 v177, v177, v0
	v_mov_b32_e32 v0, v177
	s_nop 1
	v_permlane32_swap_b32_e32 v177, v0
	v_max_f32_e32 v177, v177, v0
	v_cmp_ge_f32_e32 vcc, s90, v177
	s_cmp_eq_u64 vcc, exec
	s_cbranch_scc0 .Lmla_h3_newmax
; __device__ __forceinline__ void finishSM9(f32x16& p0, f32x16& p1, float alpha, float& l_reg, v8i32& p8) {
; #pragma unroll
;   for (int r = 0; r < 16; ++r) { p0[r] = __builtin_amdgcn_exp2f(p0[r]); p1[r] = __builtin_amdgcn_exp2f(p1[r]); }
;   float ps = 0;
; #pragma unroll
;   for (int r = 0; r < 16; ++r) ps += p0[r];
; #pragma unroll
;   for (int r = 0; r < 16; ++r) ps += p1[r];
;   { auto rr = __builtin_amdgcn_permlane32_swap(__float_as_uint(ps), __float_as_uint(ps), false, false);
;     ps = __uint_as_float(rr[0]) + __uint_as_float(rr[1]); }
;   l_reg = l_reg * alpha + ps;
; #pragma unroll
;   for (int g = 0; g < 4; ++g) {
;     int w = __builtin_amdgcn_cvt_pk_fp8_f32(p0[4 * g], p0[4 * g + 1], 0, false); p8[g] = __builtin_amdgcn_cvt_pk_fp8_f32(p0[4 * g + 2], p0[4 * g + 3], w, true);
;     int u = __builtin_amdgcn_cvt_pk_fp8_f32(p1[4 * g], p1[4 * g + 1], 0, false); p8[4 + g] = __builtin_amdgcn_cvt_pk_fp8_f32(p1[4 * g + 2], p1[4 * g + 3], u, true); }
; }
; __device__ __forceinline__ void pv8(f32x16* o, const char* Vt, const v8i32 p8, int r32, int hi) {
;   const int sw = (r32 >> 2) & 3, a0 = r32 * 64 + (((hi * 2) ^ sw) << 4), a1 = r32 * 64 + (((hi * 2 + 1) ^ sw) << 4);
; #pragma unroll
;   for (int d0 = 0; d0 < 4; ++d0) {
;     const v8i32 vf = cat8(*reinterpret_cast<const v4i32*>(Vt + d0 * 2048 + a0), *reinterpret_cast<const v4i32*>(Vt + d0 * 2048 + a1));
;     o[d0] = __builtin_amdgcn_mfma_scale_f32_32x32x64_f8f6f4(p8, vf, o[d0], 0, 0, 0, 127, 0, 127); }
; }
; __device__ __forceinline__ void qkt9(f32x16& p0, f32x16& p1, const char* Kn, const char* Kr, const v8i32* qf, const float init, int r32, int hi) {
; #pragma unroll
;   for (int r = 0; r < 16; ++r) { p0[r] = init; p1[r] = init; }
; #pragma unroll
;   for (int s = 0; s < 2; ++s) { const int c0 = s * 4 + hi * 2;
;     const v8i32 a0 = cat8(*reinterpret_cast<const v4i32*>(Kn + KN8SW(r32, c0)), *reinterpret_cast<const v4i32*>(Kn + KN8SW(r32, c0 + 1)));
;     const v8i32 a1 = cat8(*reinterpret_cast<const v4i32*>(Kn + 4096 + KN8SW(r32, c0)), *reinterpret_cast<const v4i32*>(Kn + 4096 + KN8SW(r32, c0 + 1)));
;     p0 = __builtin_amdgcn_mfma_scale_f32_32x32x64_f8f6f4(a0, qf[s], p0, 0, 0, 0, 127, 0, 124);
;     p1 = __builtin_amdgcn_mfma_scale_f32_32x32x64_f8f6f4(a1, qf[s], p1, 0, 0, 0, 127, 0, 124); }
;   { const int c0 = hi * 2;
.Lmla_h3_cont:
	ds_read_b128 v[114:117], v215 offset:51200
	ds_read_b128 v[118:121], v216 offset:51200
	ds_read_b128 v[222:225], v215 offset:55296
	ds_read_b128 v[226:229], v216 offset:55296
	global_load_dwordx4 v[158:161], v176, s[18:19]
	global_load_dwordx4 v[162:165], v178, s[16:17]
	global_load_dwordx4 v[154:157], v[180:181], off
	v_add_u32_e32 v176, 0x2000, v176
	v_add_u32_e32 v178, 0x20000, v178
	s_mov_b64 s[20:21], 0x1000
	v_lshl_add_u64 v[180:181], v[180:181], 0, s[20:21]
	v_exp_f32_e32 v0, v82
	v_exp_f32_e32 v177, v83
	v_exp_f32_e32 v179, v84
	v_exp_f32_e32 v254, v85
	v_add_f32_e32 v219, v0, v177
	v_cvt_pk_fp8_f32 v246, v0, v177
	v_add_f32_e32 v219, v179, v219
	v_add_f32_e32 v219, v254, v219
	v_cvt_pk_fp8_f32 v246, v179, v254 op_sel:[0,0,1]
	s_waitcnt lgkmcnt(2)
	v_mfma_scale_f32_32x32x64_f8f6f4 v[114:129], v[114:121], v[146:153], v[230:245], v194, v193 op_sel_hi:[0,0,0]
	v_exp_f32_e32 v0, v86
	v_exp_f32_e32 v177, v87
	v_exp_f32_e32 v179, v88
	v_exp_f32_e32 v254, v89
	v_add_f32_e32 v219, v0, v219
	v_add_f32_e32 v219, v177, v219
	v_cvt_pk_fp8_f32 v247, v0, v177
	v_add_f32_e32 v219, v179, v219
	v_add_f32_e32 v219, v254, v219
	v_cvt_pk_fp8_f32 v247, v179, v254 op_sel:[0,0,1]
	ds_read_b128 v[82:85], v213 offset:51200
	ds_read_b128 v[86:89], v214 offset:51200
	s_waitcnt lgkmcnt(2)
	v_mfma_scale_f32_32x32x64_f8f6f4 v[98:113], v[222:229], v[146:153], v[230:245], v194, v193 op_sel_hi:[0,0,0]
	ds_read_b128 v[222:225], v213 offset:55296
	ds_read_b128 v[226:229], v214 offset:55296
	v_exp_f32_e32 v0, v90
	v_exp_f32_e32 v177, v91
	v_exp_f32_e32 v179, v92
	v_exp_f32_e32 v254, v93
	v_add_f32_e32 v219, v0, v219
	v_add_f32_e32 v219, v177, v219
	v_cvt_pk_fp8_f32 v248, v0, v177
	v_add_f32_e32 v219, v179, v219
	v_add_f32_e32 v219, v254, v219
	v_cvt_pk_fp8_f32 v248, v179, v254 op_sel:[0,0,1]
	v_exp_f32_e32 v0, v94
	v_exp_f32_e32 v177, v95
	v_exp_f32_e32 v179, v96
	v_exp_f32_e32 v254, v97
	v_add_f32_e32 v219, v0, v219
	v_add_f32_e32 v219, v177, v219
	v_cvt_pk_fp8_f32 v249, v0, v177
	v_add_f32_e32 v219, v179, v219
	v_add_f32_e32 v219, v254, v219
	v_cvt_pk_fp8_f32 v249, v179, v254 op_sel:[0,0,1]
	ds_read_b128 v[90:93], v185 offset:59392
	ds_read_b128 v[94:97], v186 offset:59392
	s_waitcnt lgkmcnt(4)
	v_mfma_scale_f32_32x32x64_f8f6f4 v[114:129], v[82:89], v[138:145], v[114:129], v194, v193 op_sel_hi:[0,0,0]
	v_exp_f32_e32 v0, v66
	v_exp_f32_e32 v177, v67
	v_exp_f32_e32 v179, v68
	v_exp_f32_e32 v254, v69
	v_add_f32_e32 v219, v0, v219
	v_add_f32_e32 v219, v177, v219
	v_cvt_pk_fp8_f32 v250, v0, v177
	v_add_f32_e32 v219, v179, v219
	v_add_f32_e32 v219, v254, v219
	v_cvt_pk_fp8_f32 v250, v179, v254 op_sel:[0,0,1]
	s_waitcnt lgkmcnt(2)
	v_mfma_scale_f32_32x32x64_f8f6f4 v[98:113], v[222:229], v[138:145], v[98:113], v194, v193 op_sel_hi:[0,0,0]
	ds_read_b128 v[222:225], v185 offset:61440
	ds_read_b128 v[226:229], v186 offset:61440
	v_exp_f32_e32 v0, v70
	v_exp_f32_e32 v177, v71
	v_exp_f32_e32 v179, v72
	v_exp_f32_e32 v254, v73
	v_add_f32_e32 v219, v0, v219
	v_add_f32_e32 v219, v177, v219
	v_cvt_pk_fp8_f32 v251, v0, v177
	v_add_f32_e32 v219, v179, v219
	v_add_f32_e32 v219, v254, v219
	v_cvt_pk_fp8_f32 v251, v179, v254 op_sel:[0,0,1]
	v_exp_f32_e32 v0, v74
	v_exp_f32_e32 v177, v75
	v_exp_f32_e32 v179, v76
	v_exp_f32_e32 v254, v77
	v_add_f32_e32 v219, v0, v219
	v_add_f32_e32 v219, v177, v219
	v_cvt_pk_fp8_f32 v252, v0, v177
	v_add_f32_e32 v219, v179, v219
	v_add_f32_e32 v219, v254, v219
	v_cvt_pk_fp8_f32 v252, v179, v254 op_sel:[0,0,1]
	s_waitcnt lgkmcnt(2)
	v_mfma_scale_f32_32x32x64_f8f6f4 v[114:129], v[90:97], v[130:137], v[114:129], v194, v193 op_sel_hi:[0,0,0]
	v_exp_f32_e32 v0, v78
	v_exp_f32_e32 v177, v79
	v_exp_f32_e32 v179, v80
	v_exp_f32_e32 v254, v81
	v_add_f32_e32 v219, v0, v219
	v_add_f32_e32 v219, v177, v219
	v_cvt_pk_fp8_f32 v253, v0, v177
	v_add_f32_e32 v219, v179, v219
	v_add_f32_e32 v219, v254, v219
	v_cvt_pk_fp8_f32 v253, v179, v254 op_sel:[0,0,1]
	ds_read_b128 v[90:93], v185 offset:8192
	ds_read_b128 v[94:97], v186 offset:8192
	ds_read_b128 v[82:85], v185 offset:10240
	ds_read_b128 v[86:89], v186 offset:10240
	ds_read_b128 v[74:77], v185 offset:12288
	ds_read_b128 v[78:81], v186 offset:12288
	ds_read_b128 v[66:69], v185 offset:14336
	ds_read_b128 v[70:73], v186 offset:14336
	s_waitcnt lgkmcnt(8)
	v_mfma_scale_f32_32x32x64_f8f6f4 v[98:113], v[222:229], v[130:137], v[98:113], v194, v193 op_sel_hi:[0,0,0]
	v_mov_b32_e32 v0, v219
	s_nop 1
	v_permlane32_swap_b32_e32 v219, v0
	v_add_f32_e32 v219, v219, v0
	v_add_f32_e32 v209, v209, v219
	v_max_f32_e32 v177, v114, v115
	v_max3_f32 v177, v177, v116, v117
	v_max3_f32 v177, v177, v118, v119
	v_max3_f32 v177, v177, v120, v121
	v_max3_f32 v177, v177, v122, v123
	v_max3_f32 v177, v177, v124, v125
	v_max3_f32 v177, v177, v126, v127
	v_max3_f32 v177, v177, v128, v129
	s_waitcnt lgkmcnt(6)
	v_mfma_scale_f32_32x32x64_f8f6f4 v[50:65], v[246:253], v[90:97], v[50:65], v194, v194 op_sel_hi:[0,0,0]
	s_waitcnt lgkmcnt(4)
	v_mfma_scale_f32_32x32x64_f8f6f4 v[34:49], v[246:253], v[82:89], v[34:49], v194, v194 op_sel_hi:[0,0,0]
	s_waitcnt lgkmcnt(2)
	v_mfma_scale_f32_32x32x64_f8f6f4 v[18:33], v[246:253], v[74:81], v[18:33], v194, v194 op_sel_hi:[0,0,0]
	s_waitcnt vmcnt(0)
	ds_write_b128 v210, v[158:161]
	ds_write_b128 v211, v[162:165] offset:16384
	ds_write_b128 v212, v[154:157] offset:32768
	s_waitcnt lgkmcnt(3)
	v_mfma_scale_f32_32x32x64_f8f6f4 v[2:17], v[246:253], v[66:73], v[2:17], v194, v194 op_sel_hi:[0,0,0]
	s_waitcnt lgkmcnt(0)
	s_barrier
	v_max_f32_e32 v0, v98, v99
	v_max3_f32 v0, v0, v100, v101
	v_max3_f32 v0, v0, v102, v103
	v_max3_f32 v0, v0, v104, v105
	v_max3_f32 v0, v0, v106, v107
	v_max3_f32 v0, v0, v108, v109
	v_max3_f32 v0, v0, v110, v111
	v_max3_f32 v0, v0, v112, v113
	v_max_f32_e32 v177, v177, v0
	v_mov_b32_e32 v0, v177
	s_nop 1
	v_permlane32_swap_b32_e32 v177, v0
	v_max_f32_e32 v177, v177, v0
	v_cmp_ge_f32_e32 vcc, s90, v177
	s_cmp_eq_u64 vcc, exec
	s_cbranch_scc0 .Lmla_h4_newmax
; __device__ __forceinline__ void finishSM9(f32x16& p0, f32x16& p1, float alpha, float& l_reg, v8i32& p8) {
; #pragma unroll
;   for (int r = 0; r < 16; ++r) { p0[r] = __builtin_amdgcn_exp2f(p0[r]); p1[r] = __builtin_amdgcn_exp2f(p1[r]); }
;   float ps = 0;
; #pragma unroll
;   for (int r = 0; r < 16; ++r) ps += p0[r];
; #pragma unroll
;   for (int r = 0; r < 16; ++r) ps += p1[r];
;   { auto rr = __builtin_amdgcn_permlane32_swap(__float_as_uint(ps), __float_as_uint(ps), false, false);
;     ps = __uint_as_float(rr[0]) + __uint_as_float(rr[1]); }
;   l_reg = l_reg * alpha + ps;
; #pragma unroll
;   for (int g = 0; g < 4; ++g) {
;     int w = __builtin_amdgcn_cvt_pk_fp8_f32(p0[4 * g], p0[4 * g + 1], 0, false); p8[g] = __builtin_amdgcn_cvt_pk_fp8_f32(p0[4 * g + 2], p0[4 * g + 3], w, true);
;     int u = __builtin_amdgcn_cvt_pk_fp8_f32(p1[4 * g], p1[4 * g + 1], 0, false); p8[4 + g] = __builtin_amdgcn_cvt_pk_fp8_f32(p1[4 * g + 2], p1[4 * g + 3], u, true); }
; }
; __device__ __forceinline__ void pv8(f32x16* o, const char* Vt, const v8i32 p8, int r32, int hi) {
;   const int sw = (r32 >> 2) & 3, a0 = r32 * 64 + (((hi * 2) ^ sw) << 4), a1 = r32 * 64 + (((hi * 2 + 1) ^ sw) << 4);
; #pragma unroll
;   for (int d0 = 0; d0 < 4; ++d0) {
;     const v8i32 vf = cat8(*reinterpret_cast<const v4i32*>(Vt + d0 * 2048 + a0), *reinterpret_cast<const v4i32*>(Vt + d0 * 2048 + a1));
;     o[d0] = __builtin_amdgcn_mfma_scale_f32_32x32x64_f8f6f4(p8, vf, o[d0], 0, 0, 0, 127, 0, 127); }
; }
; __device__ __forceinline__ void qkt9(f32x16& p0, f32x16& p1, const char* Kn, const char* Kr, const v8i32* qf, const float init, int r32, int hi) {
; #pragma unroll
;   for (int r = 0; r < 16; ++r) { p0[r] = init; p1[r] = init; }
; #pragma unroll
;   for (int s = 0; s < 2; ++s) { const int c0 = s * 4 + hi * 2;
;     const v8i32 a0 = cat8(*reinterpret_cast<const v4i32*>(Kn + KN8SW(r32, c0)), *reinterpret_cast<const v4i32*>(Kn + KN8SW(r32, c0 + 1)));
;     const v8i32 a1 = cat8(*reinterpret_cast<const v4i32*>(Kn + 4096 + KN8SW(r32, c0)), *reinterpret_cast<const v4i32*>(Kn + 4096 + KN8SW(r32, c0 + 1)));
;     p0 = __builtin_amdgcn_mfma_scale_f32_32x32x64_f8f6f4(a0, qf[s], p0, 0, 0, 0, 127, 0, 124);
;     p1 = __builtin_amdgcn_mfma_scale_f32_32x32x64_f8f6f4(a1, qf[s], p1, 0, 0, 0, 127, 0, 124); }
;   { const int c0 = hi * 2;
.Lmla_h4_cont:
	ds_read_b128 v[82:85], v215 offset:16384
	ds_read_b128 v[86:89], v216 offset:16384
	ds_read_b128 v[222:225], v215 offset:20480
	ds_read_b128 v[226:229], v216 offset:20480
	global_load_dwordx4 v[158:161], v176, s[18:19]
	global_load_dwordx4 v[162:165], v178, s[16:17]
	global_load_dwordx4 v[154:157], v[180:181], off
	v_add_u32_e32 v176, 0x2000, v176
	v_add_u32_e32 v178, 0x20000, v178
	s_mov_b64 s[20:21], 0x1000
	v_lshl_add_u64 v[180:181], v[180:181], 0, s[20:21]
	v_exp_f32_e32 v0, v114
	v_exp_f32_e32 v177, v115
	v_exp_f32_e32 v179, v116
	v_exp_f32_e32 v254, v117
	v_add_f32_e32 v219, v0, v177
	v_cvt_pk_fp8_f32 v246, v0, v177
	v_add_f32_e32 v219, v179, v219
	v_add_f32_e32 v219, v254, v219
	v_cvt_pk_fp8_f32 v246, v179, v254 op_sel:[0,0,1]
	s_waitcnt lgkmcnt(2)
	v_mfma_scale_f32_32x32x64_f8f6f4 v[82:97], v[82:89], v[146:153], v[230:245], v194, v193 op_sel_hi:[0,0,0]
	v_exp_f32_e32 v0, v118
	v_exp_f32_e32 v177, v119
	v_exp_f32_e32 v179, v120
	v_exp_f32_e32 v254, v121
	v_add_f32_e32 v219, v0, v219
	v_add_f32_e32 v219, v177, v219
	v_cvt_pk_fp8_f32 v247, v0, v177
	v_add_f32_e32 v219, v179, v219
	v_add_f32_e32 v219, v254, v219
	v_cvt_pk_fp8_f32 v247, v179, v254 op_sel:[0,0,1]
	ds_read_b128 v[114:117], v213 offset:16384
	ds_read_b128 v[118:121], v214 offset:16384
	s_waitcnt lgkmcnt(2)
	v_mfma_scale_f32_32x32x64_f8f6f4 v[66:81], v[222:229], v[146:153], v[230:245], v194, v193 op_sel_hi:[0,0,0]
	ds_read_b128 v[222:225], v213 offset:20480
	ds_read_b128 v[226:229], v214 offset:20480
	v_exp_f32_e32 v0, v122
	v_exp_f32_e32 v177, v123
	v_exp_f32_e32 v179, v124
	v_exp_f32_e32 v254, v125
	v_add_f32_e32 v219, v0, v219
	v_add_f32_e32 v219, v177, v219
	v_cvt_pk_fp8_f32 v248, v0, v177
	v_add_f32_e32 v219, v179, v219
	v_add_f32_e32 v219, v254, v219
	v_cvt_pk_fp8_f32 v248, v179, v254 op_sel:[0,0,1]
	v_exp_f32_e32 v0, v126
	v_exp_f32_e32 v177, v127
	v_exp_f32_e32 v179, v128
	v_exp_f32_e32 v254, v129
	v_add_f32_e32 v219, v0, v219
	v_add_f32_e32 v219, v177, v219
	v_cvt_pk_fp8_f32 v249, v0, v177
	v_add_f32_e32 v219, v179, v219
	v_add_f32_e32 v219, v254, v219
	v_cvt_pk_fp8_f32 v249, v179, v254 op_sel:[0,0,1]
	ds_read_b128 v[122:125], v185 offset:32768
	ds_read_b128 v[126:129], v186 offset:32768
	s_waitcnt lgkmcnt(4)
	v_mfma_scale_f32_32x32x64_f8f6f4 v[82:97], v[114:121], v[138:145], v[82:97], v194, v193 op_sel_hi:[0,0,0]
	v_exp_f32_e32 v0, v98
	v_exp_f32_e32 v177, v99
	v_exp_f32_e32 v179, v100
	v_exp_f32_e32 v254, v101
	v_add_f32_e32 v219, v0, v219
	v_add_f32_e32 v219, v177, v219
	v_cvt_pk_fp8_f32 v250, v0, v177
	v_add_f32_e32 v219, v179, v219
	v_add_f32_e32 v219, v254, v219
	v_cvt_pk_fp8_f32 v250, v179, v254 op_sel:[0,0,1]
	s_waitcnt lgkmcnt(2)
	v_mfma_scale_f32_32x32x64_f8f6f4 v[66:81], v[222:229], v[138:145], v[66:81], v194, v193 op_sel_hi:[0,0,0]
	ds_read_b128 v[222:225], v185 offset:34816
	ds_read_b128 v[226:229], v186 offset:34816
	v_exp_f32_e32 v0, v102
	v_exp_f32_e32 v177, v103
	v_exp_f32_e32 v179, v104
	v_exp_f32_e32 v254, v105
	v_add_f32_e32 v219, v0, v219
	v_add_f32_e32 v219, v177, v219
	v_cvt_pk_fp8_f32 v251, v0, v177
	v_add_f32_e32 v219, v179, v219
	v_add_f32_e32 v219, v254, v219
	v_cvt_pk_fp8_f32 v251, v179, v254 op_sel:[0,0,1]
	v_exp_f32_e32 v0, v106
	v_exp_f32_e32 v177, v107
	v_exp_f32_e32 v179, v108
	v_exp_f32_e32 v254, v109
	v_add_f32_e32 v219, v0, v219
	v_add_f32_e32 v219, v177, v219
	v_cvt_pk_fp8_f32 v252, v0, v177
	v_add_f32_e32 v219, v179, v219
	v_add_f32_e32 v219, v254, v219
	v_cvt_pk_fp8_f32 v252, v179, v254 op_sel:[0,0,1]
	s_waitcnt lgkmcnt(2)
	v_mfma_scale_f32_32x32x64_f8f6f4 v[82:97], v[122:129], v[130:137], v[82:97], v194, v193 op_sel_hi:[0,0,0]
	v_exp_f32_e32 v0, v110
	v_exp_f32_e32 v177, v111
	v_exp_f32_e32 v179, v112
	v_exp_f32_e32 v254, v113
	v_add_f32_e32 v219, v0, v219
	v_add_f32_e32 v219, v177, v219
	v_cvt_pk_fp8_f32 v253, v0, v177
	v_add_f32_e32 v219, v179, v219
	v_add_f32_e32 v219, v254, v219
	v_cvt_pk_fp8_f32 v253, v179, v254 op_sel:[0,0,1]
	ds_read_b128 v[122:125], v185 offset:43008
	ds_read_b128 v[126:129], v186 offset:43008
	ds_read_b128 v[114:117], v185 offset:45056
	ds_read_b128 v[118:121], v186 offset:45056
	ds_read_b128 v[106:109], v185 offset:47104
	ds_read_b128 v[110:113], v186 offset:47104
	ds_read_b128 v[98:101], v185 offset:49152
	ds_read_b128 v[102:105], v186 offset:49152
	s_waitcnt lgkmcnt(8)
	v_mfma_scale_f32_32x32x64_f8f6f4 v[66:81], v[222:229], v[130:137], v[66:81], v194, v193 op_sel_hi:[0,0,0]
	v_mov_b32_e32 v0, v219
	s_nop 1
	v_permlane32_swap_b32_e32 v219, v0
	v_add_f32_e32 v219, v219, v0
	v_add_f32_e32 v209, v209, v219
	v_max_f32_e32 v177, v82, v83
	v_max3_f32 v177, v177, v84, v85
	v_max3_f32 v177, v177, v86, v87
	v_max3_f32 v177, v177, v88, v89
	v_max3_f32 v177, v177, v90, v91
	v_max3_f32 v177, v177, v92, v93
	v_max3_f32 v177, v177, v94, v95
	v_max3_f32 v177, v177, v96, v97
	s_waitcnt lgkmcnt(6)
	v_mfma_scale_f32_32x32x64_f8f6f4 v[50:65], v[246:253], v[122:129], v[50:65], v194, v194 op_sel_hi:[0,0,0]
	s_waitcnt lgkmcnt(4)
	v_mfma_scale_f32_32x32x64_f8f6f4 v[34:49], v[246:253], v[114:121], v[34:49], v194, v194 op_sel_hi:[0,0,0]
	s_waitcnt lgkmcnt(2)
	v_mfma_scale_f32_32x32x64_f8f6f4 v[18:33], v[246:253], v[106:113], v[18:33], v194, v194 op_sel_hi:[0,0,0]
	s_waitcnt vmcnt(0)
	ds_write_b128 v210, v[158:161] offset:8192
	ds_write_b128 v211, v[162:165] offset:24576
	ds_write_b128 v212, v[154:157] offset:36864
	s_waitcnt lgkmcnt(3)
	v_mfma_scale_f32_32x32x64_f8f6f4 v[2:17], v[246:253], v[98:105], v[2:17], v194, v194 op_sel_hi:[0,0,0]
	s_waitcnt lgkmcnt(0)
	s_barrier
	v_max_f32_e32 v0, v66, v67
	v_max3_f32 v0, v0, v68, v69
	v_max3_f32 v0, v0, v70, v71
	v_max3_f32 v0, v0, v72, v73
	v_max3_f32 v0, v0, v74, v75
	v_max3_f32 v0, v0, v76, v77
	v_max3_f32 v0, v0, v78, v79
	v_max3_f32 v0, v0, v80, v81
	v_max_f32_e32 v177, v177, v0
	v_mov_b32_e32 v0, v177
	s_nop 1
	v_permlane32_swap_b32_e32 v177, v0
	v_max_f32_e32 v177, v177, v0
	v_cmp_ge_f32_e32 vcc, s90, v177
	s_cmp_eq_u64 vcc, exec
	s_cbranch_scc0 .Lmla_h5_newmax
; __device__ __forceinline__ void finishSM9(f32x16& p0, f32x16& p1, float alpha, float& l_reg, v8i32& p8) {
; #pragma unroll
;   for (int r = 0; r < 16; ++r) { p0[r] = __builtin_amdgcn_exp2f(p0[r]); p1[r] = __builtin_amdgcn_exp2f(p1[r]); }
;   float ps = 0;
; #pragma unroll
;   for (int r = 0; r < 16; ++r) ps += p0[r];
; #pragma unroll
;   for (int r = 0; r < 16; ++r) ps += p1[r];
;   { auto rr = __builtin_amdgcn_permlane32_swap(__float_as_uint(ps), __float_as_uint(ps), false, false);
;     ps = __uint_as_float(rr[0]) + __uint_as_float(rr[1]); }
;   l_reg = l_reg * alpha + ps;
; #pragma unroll
;   for (int g = 0; g < 4; ++g) {
;     int w = __builtin_amdgcn_cvt_pk_fp8_f32(p0[4 * g], p0[4 * g + 1], 0, false); p8[g] = __builtin_amdgcn_cvt_pk_fp8_f32(p0[4 * g + 2], p0[4 * g + 3], w, true);
;     int u = __builtin_amdgcn_cvt_pk_fp8_f32(p1[4 * g], p1[4 * g + 1], 0, false); p8[4 + g] = __builtin_amdgcn_cvt_pk_fp8_f32(p1[4 * g + 2], p1[4 * g + 3], u, true); }
; }
; __device__ __forceinline__ void pv8(f32x16* o, const char* Vt, const v8i32 p8, int r32, int hi) {
;   const int sw = (r32 >> 2) & 3, a0 = r32 * 64 + (((hi * 2) ^ sw) << 4), a1 = r32 * 64 + (((hi * 2 + 1) ^ sw) << 4);
; #pragma unroll
;   for (int d0 = 0; d0 < 4; ++d0) {
;     const v8i32 vf = cat8(*reinterpret_cast<const v4i32*>(Vt + d0 * 2048 + a0), *reinterpret_cast<const v4i32*>(Vt + d0 * 2048 + a1));
;     o[d0] = __builtin_amdgcn_mfma_scale_f32_32x32x64_f8f6f4(p8, vf, o[d0], 0, 0, 0, 127, 0, 127); }
; }
; __device__ __forceinline__ void qkt9(f32x16& p0, f32x16& p1, const char* Kn, const char* Kr, const v8i32* qf, const float init, int r32, int hi) {
; #pragma unroll
;   for (int r = 0; r < 16; ++r) { p0[r] = init; p1[r] = init; }
; #pragma unroll
;   for (int s = 0; s < 2; ++s) { const int c0 = s * 4 + hi * 2;
;     const v8i32 a0 = cat8(*reinterpret_cast<const v4i32*>(Kn + KN8SW(r32, c0)), *reinterpret_cast<const v4i32*>(Kn + KN8SW(r32, c0 + 1)));
;     const v8i32 a1 = cat8(*reinterpret_cast<const v4i32*>(Kn + 4096 + KN8SW(r32, c0)), *reinterpret_cast<const v4i32*>(Kn + 4096 + KN8SW(r32, c0 + 1)));
;     p0 = __builtin_amdgcn_mfma_scale_f32_32x32x64_f8f6f4(a0, qf[s], p0, 0, 0, 0, 127, 0, 124);
;     p1 = __builtin_amdgcn_mfma_scale_f32_32x32x64_f8f6f4(a1, qf[s], p1, 0, 0, 0, 127, 0, 124); }
;   { const int c0 = hi * 2;
.Lmla_h5_cont:
	s_add_i32 s30, s30, 1
	s_cmpk_lt_u32 s30, 42
	s_cbranch_scc1 .LBB0_1321
	ds_read_b128 v[114:117], v215 offset:24576
	ds_read_b128 v[118:121], v216 offset:24576
	ds_read_b128 v[222:225], v215 offset:28672
	ds_read_b128 v[226:229], v216 offset:28672
	global_load_dwordx4 v[158:161], v176, s[18:19]
	global_load_dwordx4 v[162:165], v178, s[16:17]
	global_load_dwordx4 v[154:157], v[180:181], off
	v_add_u32_e32 v176, 0x2000, v176
	v_add_u32_e32 v178, 0x20000, v178
	s_mov_b64 s[20:21], 0x1000
	v_lshl_add_u64 v[180:181], v[180:181], 0, s[20:21]
	v_exp_f32_e32 v0, v82
	v_exp_f32_e32 v177, v83
	v_exp_f32_e32 v179, v84
	v_exp_f32_e32 v254, v85
	v_add_f32_e32 v219, v0, v177
	v_cvt_pk_fp8_f32 v246, v0, v177
	v_add_f32_e32 v219, v179, v219
	v_add_f32_e32 v219, v254, v219
	v_cvt_pk_fp8_f32 v246, v179, v254 op_sel:[0,0,1]
	s_waitcnt lgkmcnt(2)
	v_mfma_scale_f32_32x32x64_f8f6f4 v[114:129], v[114:121], v[146:153], v[230:245], v194, v193 op_sel_hi:[0,0,0]
	v_exp_f32_e32 v0, v86
	v_exp_f32_e32 v177, v87
	v_exp_f32_e32 v179, v88
	v_exp_f32_e32 v254, v89
	v_add_f32_e32 v219, v0, v219
	v_add_f32_e32 v219, v177, v219
	v_cvt_pk_fp8_f32 v247, v0, v177
	v_add_f32_e32 v219, v179, v219
	v_add_f32_e32 v219, v254, v219
	v_cvt_pk_fp8_f32 v247, v179, v254 op_sel:[0,0,1]
	ds_read_b128 v[82:85], v213 offset:24576
	ds_read_b128 v[86:89], v214 offset:24576
	s_waitcnt lgkmcnt(2)
	v_mfma_scale_f32_32x32x64_f8f6f4 v[98:113], v[222:229], v[146:153], v[230:245], v194, v193 op_sel_hi:[0,0,0]
	ds_read_b128 v[222:225], v213 offset:28672
	ds_read_b128 v[226:229], v214 offset:28672
	v_exp_f32_e32 v0, v90
	v_exp_f32_e32 v177, v91
	v_exp_f32_e32 v179, v92
	v_exp_f32_e32 v254, v93
	v_add_f32_e32 v219, v0, v219
	v_add_f32_e32 v219, v177, v219
	v_cvt_pk_fp8_f32 v248, v0, v177
	v_add_f32_e32 v219, v179, v219
	v_add_f32_e32 v219, v254, v219
	v_cvt_pk_fp8_f32 v248, v179, v254 op_sel:[0,0,1]
	v_exp_f32_e32 v0, v94
	v_exp_f32_e32 v177, v95
	v_exp_f32_e32 v179, v96
	v_exp_f32_e32 v254, v97
	v_add_f32_e32 v219, v0, v219
	v_add_f32_e32 v219, v177, v219
	v_cvt_pk_fp8_f32 v249, v0, v177
	v_add_f32_e32 v219, v179, v219
	v_add_f32_e32 v219, v254, v219
	v_cvt_pk_fp8_f32 v249, v179, v254 op_sel:[0,0,1]
	ds_read_b128 v[90:93], v185 offset:36864
	ds_read_b128 v[94:97], v186 offset:36864
	s_waitcnt lgkmcnt(4)
	v_mfma_scale_f32_32x32x64_f8f6f4 v[114:129], v[82:89], v[138:145], v[114:129], v194, v193 op_sel_hi:[0,0,0]
	v_exp_f32_e32 v0, v66
	v_exp_f32_e32 v177, v67
	v_exp_f32_e32 v179, v68
	v_exp_f32_e32 v254, v69
	v_add_f32_e32 v219, v0, v219
	v_add_f32_e32 v219, v177, v219
	v_cvt_pk_fp8_f32 v250, v0, v177
	v_add_f32_e32 v219, v179, v219
	v_add_f32_e32 v219, v254, v219
	v_cvt_pk_fp8_f32 v250, v179, v254 op_sel:[0,0,1]
	s_waitcnt lgkmcnt(2)
	v_mfma_scale_f32_32x32x64_f8f6f4 v[98:113], v[222:229], v[138:145], v[98:113], v194, v193 op_sel_hi:[0,0,0]
	ds_read_b128 v[222:225], v185 offset:38912
	ds_read_b128 v[226:229], v186 offset:38912
	v_exp_f32_e32 v0, v70
	v_exp_f32_e32 v177, v71
	v_exp_f32_e32 v179, v72
	v_exp_f32_e32 v254, v73
	v_add_f32_e32 v219, v0, v219
	v_add_f32_e32 v219, v177, v219
	v_cvt_pk_fp8_f32 v251, v0, v177
	v_add_f32_e32 v219, v179, v219
	v_add_f32_e32 v219, v254, v219
	v_cvt_pk_fp8_f32 v251, v179, v254 op_sel:[0,0,1]
	v_exp_f32_e32 v0, v74
	v_exp_f32_e32 v177, v75
	v_exp_f32_e32 v179, v76
	v_exp_f32_e32 v254, v77
	v_add_f32_e32 v219, v0, v219
	v_add_f32_e32 v219, v177, v219
	v_cvt_pk_fp8_f32 v252, v0, v177
	v_add_f32_e32 v219, v179, v219
	v_add_f32_e32 v219, v254, v219
	v_cvt_pk_fp8_f32 v252, v179, v254 op_sel:[0,0,1]
	s_waitcnt lgkmcnt(2)
	v_mfma_scale_f32_32x32x64_f8f6f4 v[114:129], v[90:97], v[130:137], v[114:129], v194, v193 op_sel_hi:[0,0,0]
	v_exp_f32_e32 v0, v78
	v_exp_f32_e32 v177, v79
	v_exp_f32_e32 v179, v80
	v_exp_f32_e32 v254, v81
	v_add_f32_e32 v219, v0, v219
	v_add_f32_e32 v219, v177, v219
	v_cvt_pk_fp8_f32 v253, v0, v177
	v_add_f32_e32 v219, v179, v219
	v_add_f32_e32 v219, v254, v219
	v_cvt_pk_fp8_f32 v253, v179, v254 op_sel:[0,0,1]
	ds_read_b128 v[90:93], v185 offset:0
	ds_read_b128 v[94:97], v186 offset:0
	ds_read_b128 v[82:85], v185 offset:2048
	ds_read_b128 v[86:89], v186 offset:2048
	ds_read_b128 v[74:77], v185 offset:4096
	ds_read_b128 v[78:81], v186 offset:4096
	ds_read_b128 v[66:69], v185 offset:6144
	ds_read_b128 v[70:73], v186 offset:6144
	s_waitcnt lgkmcnt(8)
	v_mfma_scale_f32_32x32x64_f8f6f4 v[98:113], v[222:229], v[130:137], v[98:113], v194, v193 op_sel_hi:[0,0,0]
	v_mov_b32_e32 v0, v219
	s_nop 1
	v_permlane32_swap_b32_e32 v219, v0
	v_add_f32_e32 v219, v219, v0
	v_add_f32_e32 v209, v209, v219
	v_max_f32_e32 v177, v114, v115
	v_max3_f32 v177, v177, v116, v117
	v_max3_f32 v177, v177, v118, v119
	v_max3_f32 v177, v177, v120, v121
	v_max3_f32 v177, v177, v122, v123
	v_max3_f32 v177, v177, v124, v125
	v_max3_f32 v177, v177, v126, v127
	v_max3_f32 v177, v177, v128, v129
	s_waitcnt lgkmcnt(6)
	v_mfma_scale_f32_32x32x64_f8f6f4 v[50:65], v[246:253], v[90:97], v[50:65], v194, v194 op_sel_hi:[0,0,0]
	s_waitcnt lgkmcnt(4)
	v_mfma_scale_f32_32x32x64_f8f6f4 v[34:49], v[246:253], v[82:89], v[34:49], v194, v194 op_sel_hi:[0,0,0]
	s_waitcnt lgkmcnt(2)
	v_mfma_scale_f32_32x32x64_f8f6f4 v[18:33], v[246:253], v[74:81], v[18:33], v194, v194 op_sel_hi:[0,0,0]
	s_waitcnt vmcnt(0)
	ds_write_b128 v210, v[158:161] offset:43008
	ds_write_b128 v211, v[162:165] offset:51200
	ds_write_b128 v212, v[154:157] offset:59392
	s_waitcnt lgkmcnt(3)
	v_mfma_scale_f32_32x32x64_f8f6f4 v[2:17], v[246:253], v[66:73], v[2:17], v194, v194 op_sel_hi:[0,0,0]
	s_waitcnt lgkmcnt(0)
	s_barrier
	v_max_f32_e32 v0, v98, v99
	v_max3_f32 v0, v0, v100, v101
	v_max3_f32 v0, v0, v102, v103
	v_max3_f32 v0, v0, v104, v105
	v_max3_f32 v0, v0, v106, v107
	v_max3_f32 v0, v0, v108, v109
	v_max3_f32 v0, v0, v110, v111
	v_max3_f32 v0, v0, v112, v113
	v_max_f32_e32 v177, v177, v0
	v_mov_b32_e32 v0, v177
	s_nop 1
	v_permlane32_swap_b32_e32 v177, v0
	v_max_f32_e32 v177, v177, v0
	v_cmp_ge_f32_e32 vcc, s90, v177
	s_cmp_eq_u64 vcc, exec
	s_cbranch_scc0 .Lmla_p0_newmax

; __device__ __forceinline__ void finishSM9(f32x16& p0, f32x16& p1, float alpha, float& l_reg, v8i32& p8) {
; #pragma unroll
;   for (int r = 0; r < 16; ++r) { p0[r] = __builtin_amdgcn_exp2f(p0[r]); p1[r] = __builtin_amdgcn_exp2f(p1[r]); }
;   float ps = 0;
; #pragma unroll
;   for (int r = 0; r < 16; ++r) ps += p0[r];
; #pragma unroll
;   for (int r = 0; r < 16; ++r) ps += p1[r];
;   { auto rr = __builtin_amdgcn_permlane32_swap(__float_as_uint(ps), __float_as_uint(ps), false, false);
;     ps = __uint_as_float(rr[0]) + __uint_as_float(rr[1]); }
;   l_reg = l_reg * alpha + ps;
; #pragma unroll
;   for (int g = 0; g < 4; ++g) {
;     int w = __builtin_amdgcn_cvt_pk_fp8_f32(p0[4 * g], p0[4 * g + 1], 0, false); p8[g] = __builtin_amdgcn_cvt_pk_fp8_f32(p0[4 * g + 2], p0[4 * g + 3], w, true);
;     int u = __builtin_amdgcn_cvt_pk_fp8_f32(p1[4 * g], p1[4 * g + 1], 0, false); p8[4 + g] = __builtin_amdgcn_cvt_pk_fp8_f32(p1[4 * g + 2], p1[4 * g + 3], u, true); }
; }
; __device__ __forceinline__ void pv8(f32x16* o, const char* Vt, const v8i32 p8, int r32, int hi) {
;   const int sw = (r32 >> 2) & 3, a0 = r32 * 64 + (((hi * 2) ^ sw) << 4), a1 = r32 * 64 + (((hi * 2 + 1) ^ sw) << 4);
; #pragma unroll
;   for (int d0 = 0; d0 < 4; ++d0) {
;     const v8i32 vf = cat8(*reinterpret_cast<const v4i32*>(Vt + d0 * 2048 + a0), *reinterpret_cast<const v4i32*>(Vt + d0 * 2048 + a1));
;     o[d0] = __builtin_amdgcn_mfma_scale_f32_32x32x64_f8f6f4(p8, vf, o[d0], 0, 0, 0, 127, 0, 127); }
; }
; __device__ __forceinline__ void qkt9(f32x16& p0, f32x16& p1, const char* Kn, const char* Kr, const v8i32* qf, const float init, int r32, int hi) {
; #pragma unroll
;   for (int r = 0; r < 16; ++r) { p0[r] = init; p1[r] = init; }
; #pragma unroll
;   for (int s = 0; s < 2; ++s) { const int c0 = s * 4 + hi * 2;
;     const v8i32 a0 = cat8(*reinterpret_cast<const v4i32*>(Kn + KN8SW(r32, c0)), *reinterpret_cast<const v4i32*>(Kn + KN8SW(r32, c0 + 1)));
;     const v8i32 a1 = cat8(*reinterpret_cast<const v4i32*>(Kn + 4096 + KN8SW(r32, c0)), *reinterpret_cast<const v4i32*>(Kn + 4096 + KN8SW(r32, c0 + 1)));
;     p0 = __builtin_amdgcn_mfma_scale_f32_32x32x64_f8f6f4(a0, qf[s], p0, 0, 0, 0, 127, 0, 124);
;     p1 = __builtin_amdgcn_mfma_scale_f32_32x32x64_f8f6f4(a1, qf[s], p1, 0, 0, 0, 127, 0, 124); }
;   { const int c0 = hi * 2;
.Lmla_stag_loop:
	ds_read_b128 v[114:117], v215 offset:24576
	ds_read_b128 v[118:121], v216 offset:24576
	ds_read_b128 v[222:225], v215 offset:28672
	ds_read_b128 v[226:229], v216 offset:28672
	v_exp_f32_e32 v0, v82
	v_exp_f32_e32 v177, v83
	v_exp_f32_e32 v179, v84
	v_exp_f32_e32 v254, v85
	v_add_f32_e32 v219, v0, v177
	v_cvt_pk_fp8_f32 v246, v0, v177
	v_add_f32_e32 v219, v179, v219
	v_add_f32_e32 v219, v254, v219
	v_cvt_pk_fp8_f32 v246, v179, v254 op_sel:[0,0,1]
	s_waitcnt lgkmcnt(2)
	v_mfma_scale_f32_32x32x64_f8f6f4 v[114:129], v[114:121], v[146:153], v[230:245], v194, v193 op_sel_hi:[0,0,0]
	v_exp_f32_e32 v0, v86
	v_exp_f32_e32 v177, v87
	v_exp_f32_e32 v179, v88
	v_exp_f32_e32 v254, v89
	v_add_f32_e32 v219, v0, v219
	v_add_f32_e32 v219, v177, v219
	v_cvt_pk_fp8_f32 v247, v0, v177
	v_add_f32_e32 v219, v179, v219
	v_add_f32_e32 v219, v254, v219
	v_cvt_pk_fp8_f32 v247, v179, v254 op_sel:[0,0,1]
	ds_read_b128 v[82:85], v213 offset:24576
	ds_read_b128 v[86:89], v214 offset:24576
	s_waitcnt lgkmcnt(2)
	v_mfma_scale_f32_32x32x64_f8f6f4 v[98:113], v[222:229], v[146:153], v[230:245], v194, v193 op_sel_hi:[0,0,0]
	ds_read_b128 v[222:225], v213 offset:28672
	ds_read_b128 v[226:229], v214 offset:28672
	v_exp_f32_e32 v0, v90
	v_exp_f32_e32 v177, v91
	v_exp_f32_e32 v179, v92
	v_exp_f32_e32 v254, v93
	v_add_f32_e32 v219, v0, v219
	v_add_f32_e32 v219, v177, v219
	v_cvt_pk_fp8_f32 v248, v0, v177
	v_add_f32_e32 v219, v179, v219
	v_add_f32_e32 v219, v254, v219
	v_cvt_pk_fp8_f32 v248, v179, v254 op_sel:[0,0,1]
	v_exp_f32_e32 v0, v94
	v_exp_f32_e32 v177, v95
	v_exp_f32_e32 v179, v96
	v_exp_f32_e32 v254, v97
	v_add_f32_e32 v219, v0, v219
	v_add_f32_e32 v219, v177, v219
	v_cvt_pk_fp8_f32 v249, v0, v177
	v_add_f32_e32 v219, v179, v219
	v_add_f32_e32 v219, v254, v219
	v_cvt_pk_fp8_f32 v249, v179, v254 op_sel:[0,0,1]
	ds_read_b128 v[90:93], v185 offset:36864
	ds_read_b128 v[94:97], v186 offset:36864
	s_waitcnt lgkmcnt(4)
	v_mfma_scale_f32_32x32x64_f8f6f4 v[114:129], v[82:89], v[138:145], v[114:129], v194, v193 op_sel_hi:[0,0,0]
	v_exp_f32_e32 v0, v66
	v_exp_f32_e32 v177, v67
	v_exp_f32_e32 v179, v68
	v_exp_f32_e32 v254, v69
	v_add_f32_e32 v219, v0, v219
	v_add_f32_e32 v219, v177, v219
	v_cvt_pk_fp8_f32 v250, v0, v177
	v_add_f32_e32 v219, v179, v219
	v_add_f32_e32 v219, v254, v219
	v_cvt_pk_fp8_f32 v250, v179, v254 op_sel:[0,0,1]
	s_waitcnt lgkmcnt(2)
	v_mfma_scale_f32_32x32x64_f8f6f4 v[98:113], v[222:229], v[138:145], v[98:113], v194, v193 op_sel_hi:[0,0,0]
	ds_read_b128 v[222:225], v185 offset:38912
	ds_read_b128 v[226:229], v186 offset:38912
	v_exp_f32_e32 v0, v70
	v_exp_f32_e32 v177, v71
	v_exp_f32_e32 v179, v72
	v_exp_f32_e32 v254, v73
	v_add_f32_e32 v219, v0, v219
	v_add_f32_e32 v219, v177, v219
	v_cvt_pk_fp8_f32 v251, v0, v177
	v_add_f32_e32 v219, v179, v219
	v_add_f32_e32 v219, v254, v219
	v_cvt_pk_fp8_f32 v251, v179, v254 op_sel:[0,0,1]
	v_exp_f32_e32 v0, v74
	v_exp_f32_e32 v177, v75
	v_exp_f32_e32 v179, v76
	v_exp_f32_e32 v254, v77
	v_add_f32_e32 v219, v0, v219
	v_add_f32_e32 v219, v177, v219
	v_cvt_pk_fp8_f32 v252, v0, v177
	v_add_f32_e32 v219, v179, v219
	v_add_f32_e32 v219, v254, v219
	v_cvt_pk_fp8_f32 v252, v179, v254 op_sel:[0,0,1]
	s_waitcnt lgkmcnt(2)
	v_mfma_scale_f32_32x32x64_f8f6f4 v[114:129], v[90:97], v[130:137], v[114:129], v194, v193 op_sel_hi:[0,0,0]
	v_exp_f32_e32 v0, v78
	v_exp_f32_e32 v177, v79
	v_exp_f32_e32 v179, v80
	v_exp_f32_e32 v254, v81
	v_add_f32_e32 v219, v0, v219
	v_add_f32_e32 v219, v177, v219
	v_cvt_pk_fp8_f32 v253, v0, v177
	v_add_f32_e32 v219, v179, v219
	v_add_f32_e32 v219, v254, v219
	v_cvt_pk_fp8_f32 v253, v179, v254 op_sel:[0,0,1]
	ds_read_b128 v[90:93], v185 offset:0
	ds_read_b128 v[94:97], v186 offset:0
	ds_read_b128 v[82:85], v185 offset:2048
	ds_read_b128 v[86:89], v186 offset:2048
	ds_read_b128 v[74:77], v185 offset:4096
	ds_read_b128 v[78:81], v186 offset:4096
	ds_read_b128 v[66:69], v185 offset:6144
	ds_read_b128 v[70:73], v186 offset:6144
	s_waitcnt lgkmcnt(8)
	v_mfma_scale_f32_32x32x64_f8f6f4 v[98:113], v[222:229], v[130:137], v[98:113], v194, v193 op_sel_hi:[0,0,0]
	v_mov_b32_e32 v0, v219
	s_nop 1
	v_permlane32_swap_b32_e32 v219, v0
	v_add_f32_e32 v219, v219, v0
	v_add_f32_e32 v209, v209, v219
	v_max_f32_e32 v177, v114, v115
	v_max3_f32 v177, v177, v116, v117
	v_max3_f32 v177, v177, v118, v119
	v_max3_f32 v177, v177, v120, v121
	v_max3_f32 v177, v177, v122, v123
	v_max3_f32 v177, v177, v124, v125
	v_max3_f32 v177, v177, v126, v127
	v_max3_f32 v177, v177, v128, v129
	s_waitcnt lgkmcnt(6)
	v_mfma_scale_f32_32x32x64_f8f6f4 v[50:65], v[246:253], v[90:97], v[50:65], v194, v194 op_sel_hi:[0,0,0]
	s_waitcnt vmcnt(0)
	ds_write_b128 v210, v[158:161] offset:43008
	ds_write_b128 v211, v[162:165] offset:51200
	s_waitcnt lgkmcnt(6)
	v_mfma_scale_f32_32x32x64_f8f6f4 v[34:49], v[246:253], v[82:89], v[34:49], v194, v194 op_sel_hi:[0,0,0]
	s_waitcnt lgkmcnt(0)
	s_barrier
	s_waitcnt lgkmcnt(2)
	v_mfma_scale_f32_32x32x64_f8f6f4 v[18:33], v[246:253], v[74:81], v[18:33], v194, v194 op_sel_hi:[0,0,0]
	global_load_dwordx4 v[158:161], v176, s[18:19]
	global_load_dwordx4 v[162:165], v178, s[16:17]
	v_add_u32_e32 v176, 0x2000, v176
	v_add_u32_e32 v178, 0x20000, v178
	s_waitcnt lgkmcnt(0)
	v_mfma_scale_f32_32x32x64_f8f6f4 v[2:17], v[246:253], v[66:73], v[2:17], v194, v194 op_sel_hi:[0,0,0]
	v_max_f32_e32 v0, v98, v99
	v_max3_f32 v0, v0, v100, v101
	v_max3_f32 v0, v0, v102, v103
	v_max3_f32 v0, v0, v104, v105
	v_max3_f32 v0, v0, v106, v107
	v_max3_f32 v0, v0, v108, v109
	v_max3_f32 v0, v0, v110, v111
	v_max3_f32 v0, v0, v112, v113
	v_max_f32_e32 v177, v177, v0
	v_mov_b32_e32 v0, v177
	s_nop 1
	v_permlane32_swap_b32_e32 v177, v0
	v_max_f32_e32 v177, v177, v0
	v_cmp_ge_f32_e32 vcc, s90, v177
	s_cmp_eq_u64 vcc, exec
	s_cbranch_scc0 .Lmla_s0_newmax
; __device__ __forceinline__ void finishSM9(f32x16& p0, f32x16& p1, float alpha, float& l_reg, v8i32& p8) {
; #pragma unroll
;   for (int r = 0; r < 16; ++r) { p0[r] = __builtin_amdgcn_exp2f(p0[r]); p1[r] = __builtin_amdgcn_exp2f(p1[r]); }
;   float ps = 0;
; #pragma unroll
;   for (int r = 0; r < 16; ++r) ps += p0[r];
; #pragma unroll
;   for (int r = 0; r < 16; ++r) ps += p1[r];
;   { auto rr = __builtin_amdgcn_permlane32_swap(__float_as_uint(ps), __float_as_uint(ps), false, false);
;     ps = __uint_as_float(rr[0]) + __uint_as_float(rr[1]); }
;   l_reg = l_reg * alpha + ps;
; #pragma unroll
;   for (int g = 0; g < 4; ++g) {
;     int w = __builtin_amdgcn_cvt_pk_fp8_f32(p0[4 * g], p0[4 * g + 1], 0, false); p8[g] = __builtin_amdgcn_cvt_pk_fp8_f32(p0[4 * g + 2], p0[4 * g + 3], w, true);
;     int u = __builtin_amdgcn_cvt_pk_fp8_f32(p1[4 * g], p1[4 * g + 1], 0, false); p8[4 + g] = __builtin_amdgcn_cvt_pk_fp8_f32(p1[4 * g + 2], p1[4 * g + 3], u, true); }
; }
; __device__ __forceinline__ void pv8(f32x16* o, const char* Vt, const v8i32 p8, int r32, int hi) {
;   const int sw = (r32 >> 2) & 3, a0 = r32 * 64 + (((hi * 2) ^ sw) << 4), a1 = r32 * 64 + (((hi * 2 + 1) ^ sw) << 4);
; #pragma unroll
;   for (int d0 = 0; d0 < 4; ++d0) {
;     const v8i32 vf = cat8(*reinterpret_cast<const v4i32*>(Vt + d0 * 2048 + a0), *reinterpret_cast<const v4i32*>(Vt + d0 * 2048 + a1));
;     o[d0] = __builtin_amdgcn_mfma_scale_f32_32x32x64_f8f6f4(p8, vf, o[d0], 0, 0, 0, 127, 0, 127); }
; }
; __device__ __forceinline__ void qkt9(f32x16& p0, f32x16& p1, const char* Kn, const char* Kr, const v8i32* qf, const float init, int r32, int hi) {
; #pragma unroll
;   for (int r = 0; r < 16; ++r) { p0[r] = init; p1[r] = init; }
; #pragma unroll
;   for (int s = 0; s < 2; ++s) { const int c0 = s * 4 + hi * 2;
;     const v8i32 a0 = cat8(*reinterpret_cast<const v4i32*>(Kn + KN8SW(r32, c0)), *reinterpret_cast<const v4i32*>(Kn + KN8SW(r32, c0 + 1)));
;     const v8i32 a1 = cat8(*reinterpret_cast<const v4i32*>(Kn + 4096 + KN8SW(r32, c0)), *reinterpret_cast<const v4i32*>(Kn + 4096 + KN8SW(r32, c0 + 1)));
;     p0 = __builtin_amdgcn_mfma_scale_f32_32x32x64_f8f6f4(a0, qf[s], p0, 0, 0, 0, 127, 0, 124);
;     p1 = __builtin_amdgcn_mfma_scale_f32_32x32x64_f8f6f4(a1, qf[s], p1, 0, 0, 0, 127, 0, 124); }
;   { const int c0 = hi * 2;
.Lmla_s0_cont:
	ds_read_b128 v[82:85], v215 offset:51200
	ds_read_b128 v[86:89], v216 offset:51200
	ds_read_b128 v[222:225], v215 offset:55296
	ds_read_b128 v[226:229], v216 offset:55296
	v_exp_f32_e32 v0, v114
	v_exp_f32_e32 v177, v115
	v_exp_f32_e32 v179, v116
	v_exp_f32_e32 v254, v117
	v_add_f32_e32 v219, v0, v177
	v_cvt_pk_fp8_f32 v246, v0, v177
	v_add_f32_e32 v219, v179, v219
	v_add_f32_e32 v219, v254, v219
	v_cvt_pk_fp8_f32 v246, v179, v254 op_sel:[0,0,1]
	s_waitcnt lgkmcnt(2)
	v_mfma_scale_f32_32x32x64_f8f6f4 v[82:97], v[82:89], v[146:153], v[230:245], v194, v193 op_sel_hi:[0,0,0]
	v_exp_f32_e32 v0, v118
	v_exp_f32_e32 v177, v119
	v_exp_f32_e32 v179, v120
	v_exp_f32_e32 v254, v121
	v_add_f32_e32 v219, v0, v219
	v_add_f32_e32 v219, v177, v219
	v_cvt_pk_fp8_f32 v247, v0, v177
	v_add_f32_e32 v219, v179, v219
	v_add_f32_e32 v219, v254, v219
	v_cvt_pk_fp8_f32 v247, v179, v254 op_sel:[0,0,1]
	ds_read_b128 v[114:117], v213 offset:51200
	ds_read_b128 v[118:121], v214 offset:51200
	s_waitcnt lgkmcnt(2)
	v_mfma_scale_f32_32x32x64_f8f6f4 v[66:81], v[222:229], v[146:153], v[230:245], v194, v193 op_sel_hi:[0,0,0]
	ds_read_b128 v[222:225], v213 offset:55296
	ds_read_b128 v[226:229], v214 offset:55296
	v_exp_f32_e32 v0, v122
	v_exp_f32_e32 v177, v123
	v_exp_f32_e32 v179, v124
	v_exp_f32_e32 v254, v125
	v_add_f32_e32 v219, v0, v219
	v_add_f32_e32 v219, v177, v219
	v_cvt_pk_fp8_f32 v248, v0, v177
	v_add_f32_e32 v219, v179, v219
	v_add_f32_e32 v219, v254, v219
	v_cvt_pk_fp8_f32 v248, v179, v254 op_sel:[0,0,1]
	v_exp_f32_e32 v0, v126
	v_exp_f32_e32 v177, v127
	v_exp_f32_e32 v179, v128
	v_exp_f32_e32 v254, v129
	v_add_f32_e32 v219, v0, v219
	v_add_f32_e32 v219, v177, v219
	v_cvt_pk_fp8_f32 v249, v0, v177
	v_add_f32_e32 v219, v179, v219
	v_add_f32_e32 v219, v254, v219
	v_cvt_pk_fp8_f32 v249, v179, v254 op_sel:[0,0,1]
	ds_read_b128 v[122:125], v185 offset:59392
	ds_read_b128 v[126:129], v186 offset:59392
	s_waitcnt lgkmcnt(4)
	v_mfma_scale_f32_32x32x64_f8f6f4 v[82:97], v[114:121], v[138:145], v[82:97], v194, v193 op_sel_hi:[0,0,0]
	v_exp_f32_e32 v0, v98
	v_exp_f32_e32 v177, v99
	v_exp_f32_e32 v179, v100
	v_exp_f32_e32 v254, v101
	v_add_f32_e32 v219, v0, v219
	v_add_f32_e32 v219, v177, v219
	v_cvt_pk_fp8_f32 v250, v0, v177
	v_add_f32_e32 v219, v179, v219
	v_add_f32_e32 v219, v254, v219
	v_cvt_pk_fp8_f32 v250, v179, v254 op_sel:[0,0,1]
	s_waitcnt lgkmcnt(2)
	v_mfma_scale_f32_32x32x64_f8f6f4 v[66:81], v[222:229], v[138:145], v[66:81], v194, v193 op_sel_hi:[0,0,0]
	ds_read_b128 v[222:225], v185 offset:61440
	ds_read_b128 v[226:229], v186 offset:61440
	v_exp_f32_e32 v0, v102
	v_exp_f32_e32 v177, v103
	v_exp_f32_e32 v179, v104
	v_exp_f32_e32 v254, v105
	v_add_f32_e32 v219, v0, v219
	v_add_f32_e32 v219, v177, v219
	v_cvt_pk_fp8_f32 v251, v0, v177
	v_add_f32_e32 v219, v179, v219
	v_add_f32_e32 v219, v254, v219
	v_cvt_pk_fp8_f32 v251, v179, v254 op_sel:[0,0,1]
	v_exp_f32_e32 v0, v106
	v_exp_f32_e32 v177, v107
	v_exp_f32_e32 v179, v108
	v_exp_f32_e32 v254, v109
	v_add_f32_e32 v219, v0, v219
	v_add_f32_e32 v219, v177, v219
	v_cvt_pk_fp8_f32 v252, v0, v177
	v_add_f32_e32 v219, v179, v219
	v_add_f32_e32 v219, v254, v219
	v_cvt_pk_fp8_f32 v252, v179, v254 op_sel:[0,0,1]
	s_waitcnt lgkmcnt(2)
	v_mfma_scale_f32_32x32x64_f8f6f4 v[82:97], v[122:129], v[130:137], v[82:97], v194, v193 op_sel_hi:[0,0,0]
	v_exp_f32_e32 v0, v110
	v_exp_f32_e32 v177, v111
	v_exp_f32_e32 v179, v112
	v_exp_f32_e32 v254, v113
	v_add_f32_e32 v219, v0, v219
	v_add_f32_e32 v219, v177, v219
	v_cvt_pk_fp8_f32 v253, v0, v177
	v_add_f32_e32 v219, v179, v219
	v_add_f32_e32 v219, v254, v219
	v_cvt_pk_fp8_f32 v253, v179, v254 op_sel:[0,0,1]
	ds_read_b128 v[122:125], v185 offset:8192
	ds_read_b128 v[126:129], v186 offset:8192
	ds_read_b128 v[114:117], v185 offset:10240
	ds_read_b128 v[118:121], v186 offset:10240
	ds_read_b128 v[106:109], v185 offset:12288
	ds_read_b128 v[110:113], v186 offset:12288
	ds_read_b128 v[98:101], v185 offset:14336
	ds_read_b128 v[102:105], v186 offset:14336
	s_waitcnt lgkmcnt(8)
	v_mfma_scale_f32_32x32x64_f8f6f4 v[66:81], v[222:229], v[130:137], v[66:81], v194, v193 op_sel_hi:[0,0,0]
	v_mov_b32_e32 v0, v219
	s_nop 1
	v_permlane32_swap_b32_e32 v219, v0
	v_add_f32_e32 v219, v219, v0
	v_add_f32_e32 v209, v209, v219
	v_max_f32_e32 v177, v82, v83
	v_max3_f32 v177, v177, v84, v85
	v_max3_f32 v177, v177, v86, v87
	v_max3_f32 v177, v177, v88, v89
	v_max3_f32 v177, v177, v90, v91
	v_max3_f32 v177, v177, v92, v93
	v_max3_f32 v177, v177, v94, v95
	v_max3_f32 v177, v177, v96, v97
	s_waitcnt lgkmcnt(6)
	v_mfma_scale_f32_32x32x64_f8f6f4 v[50:65], v[246:253], v[122:129], v[50:65], v194, v194 op_sel_hi:[0,0,0]
	s_waitcnt vmcnt(0)
	ds_write_b128 v210, v[158:161]
	ds_write_b128 v211, v[162:165] offset:16384
	s_waitcnt lgkmcnt(6)
	v_mfma_scale_f32_32x32x64_f8f6f4 v[34:49], v[246:253], v[114:121], v[34:49], v194, v194 op_sel_hi:[0,0,0]
	s_waitcnt lgkmcnt(0)
	s_barrier
	s_waitcnt lgkmcnt(2)
	v_mfma_scale_f32_32x32x64_f8f6f4 v[18:33], v[246:253], v[106:113], v[18:33], v194, v194 op_sel_hi:[0,0,0]
	global_load_dwordx4 v[158:161], v176, s[18:19]
	global_load_dwordx4 v[162:165], v178, s[16:17]
	v_add_u32_e32 v176, 0x2000, v176
	v_add_u32_e32 v178, 0x20000, v178
	s_waitcnt lgkmcnt(0)
	v_mfma_scale_f32_32x32x64_f8f6f4 v[2:17], v[246:253], v[98:105], v[2:17], v194, v194 op_sel_hi:[0,0,0]
	v_max_f32_e32 v0, v66, v67
	v_max3_f32 v0, v0, v68, v69
	v_max3_f32 v0, v0, v70, v71
	v_max3_f32 v0, v0, v72, v73
	v_max3_f32 v0, v0, v74, v75
	v_max3_f32 v0, v0, v76, v77
	v_max3_f32 v0, v0, v78, v79
	v_max3_f32 v0, v0, v80, v81
	v_max_f32_e32 v177, v177, v0
	v_mov_b32_e32 v0, v177
	s_nop 1
	v_permlane32_swap_b32_e32 v177, v0
	v_max_f32_e32 v177, v177, v0
	v_cmp_ge_f32_e32 vcc, s90, v177
	s_cmp_eq_u64 vcc, exec
	s_cbranch_scc0 .Lmla_s1_newmax
; __device__ __forceinline__ void finishSM9(f32x16& p0, f32x16& p1, float alpha, float& l_reg, v8i32& p8) {
; #pragma unroll
;   for (int r = 0; r < 16; ++r) { p0[r] = __builtin_amdgcn_exp2f(p0[r]); p1[r] = __builtin_amdgcn_exp2f(p1[r]); }
;   float ps = 0;
; #pragma unroll
;   for (int r = 0; r < 16; ++r) ps += p0[r];
; #pragma unroll
;   for (int r = 0; r < 16; ++r) ps += p1[r];
;   { auto rr = __builtin_amdgcn_permlane32_swap(__float_as_uint(ps), __float_as_uint(ps), false, false);
;     ps = __uint_as_float(rr[0]) + __uint_as_float(rr[1]); }
;   l_reg = l_reg * alpha + ps;
; #pragma unroll
;   for (int g = 0; g < 4; ++g) {
;     int w = __builtin_amdgcn_cvt_pk_fp8_f32(p0[4 * g], p0[4 * g + 1], 0, false); p8[g] = __builtin_amdgcn_cvt_pk_fp8_f32(p0[4 * g + 2], p0[4 * g + 3], w, true);
;     int u = __builtin_amdgcn_cvt_pk_fp8_f32(p1[4 * g], p1[4 * g + 1], 0, false); p8[4 + g] = __builtin_amdgcn_cvt_pk_fp8_f32(p1[4 * g + 2], p1[4 * g + 3], u, true); }
; }
; __device__ __forceinline__ void pv8(f32x16* o, const char* Vt, const v8i32 p8, int r32, int hi) {
;   const int sw = (r32 >> 2) & 3, a0 = r32 * 64 + (((hi * 2) ^ sw) << 4), a1 = r32 * 64 + (((hi * 2 + 1) ^ sw) << 4);
; #pragma unroll
;   for (int d0 = 0; d0 < 4; ++d0) {
;     const v8i32 vf = cat8(*reinterpret_cast<const v4i32*>(Vt + d0 * 2048 + a0), *reinterpret_cast<const v4i32*>(Vt + d0 * 2048 + a1));
;     o[d0] = __builtin_amdgcn_mfma_scale_f32_32x32x64_f8f6f4(p8, vf, o[d0], 0, 0, 0, 127, 0, 127); }
; }
; __device__ __forceinline__ void qkt9(f32x16& p0, f32x16& p1, const char* Kn, const char* Kr, const v8i32* qf, const float init, int r32, int hi) {
; #pragma unroll
;   for (int r = 0; r < 16; ++r) { p0[r] = init; p1[r] = init; }
; #pragma unroll
;   for (int s = 0; s < 2; ++s) { const int c0 = s * 4 + hi * 2;
;     const v8i32 a0 = cat8(*reinterpret_cast<const v4i32*>(Kn + KN8SW(r32, c0)), *reinterpret_cast<const v4i32*>(Kn + KN8SW(r32, c0 + 1)));
;     const v8i32 a1 = cat8(*reinterpret_cast<const v4i32*>(Kn + 4096 + KN8SW(r32, c0)), *reinterpret_cast<const v4i32*>(Kn + 4096 + KN8SW(r32, c0 + 1)));
;     p0 = __builtin_amdgcn_mfma_scale_f32_32x32x64_f8f6f4(a0, qf[s], p0, 0, 0, 0, 127, 0, 124);
;     p1 = __builtin_amdgcn_mfma_scale_f32_32x32x64_f8f6f4(a1, qf[s], p1, 0, 0, 0, 127, 0, 124); }
;   { const int c0 = hi * 2;
.Lmla_s1_cont:
	ds_read_b128 v[114:117], v215 offset:16384
	ds_read_b128 v[118:121], v216 offset:16384
	ds_read_b128 v[222:225], v215 offset:20480
	ds_read_b128 v[226:229], v216 offset:20480
	v_exp_f32_e32 v0, v82
	v_exp_f32_e32 v177, v83
	v_exp_f32_e32 v179, v84
	v_exp_f32_e32 v254, v85
	v_add_f32_e32 v219, v0, v177
	v_cvt_pk_fp8_f32 v246, v0, v177
	v_add_f32_e32 v219, v179, v219
	v_add_f32_e32 v219, v254, v219
	v_cvt_pk_fp8_f32 v246, v179, v254 op_sel:[0,0,1]
	s_waitcnt lgkmcnt(2)
	v_mfma_scale_f32_32x32x64_f8f6f4 v[114:129], v[114:121], v[146:153], v[230:245], v194, v193 op_sel_hi:[0,0,0]
	v_exp_f32_e32 v0, v86
	v_exp_f32_e32 v177, v87
	v_exp_f32_e32 v179, v88
	v_exp_f32_e32 v254, v89
	v_add_f32_e32 v219, v0, v219
	v_add_f32_e32 v219, v177, v219
	v_cvt_pk_fp8_f32 v247, v0, v177
	v_add_f32_e32 v219, v179, v219
	v_add_f32_e32 v219, v254, v219
	v_cvt_pk_fp8_f32 v247, v179, v254 op_sel:[0,0,1]
	ds_read_b128 v[82:85], v213 offset:16384
	ds_read_b128 v[86:89], v214 offset:16384
	s_waitcnt lgkmcnt(2)
	v_mfma_scale_f32_32x32x64_f8f6f4 v[98:113], v[222:229], v[146:153], v[230:245], v194, v193 op_sel_hi:[0,0,0]
	ds_read_b128 v[222:225], v213 offset:20480
	ds_read_b128 v[226:229], v214 offset:20480
	v_exp_f32_e32 v0, v90
	v_exp_f32_e32 v177, v91
	v_exp_f32_e32 v179, v92
	v_exp_f32_e32 v254, v93
	v_add_f32_e32 v219, v0, v219
	v_add_f32_e32 v219, v177, v219
	v_cvt_pk_fp8_f32 v248, v0, v177
	v_add_f32_e32 v219, v179, v219
	v_add_f32_e32 v219, v254, v219
	v_cvt_pk_fp8_f32 v248, v179, v254 op_sel:[0,0,1]
	v_exp_f32_e32 v0, v94
	v_exp_f32_e32 v177, v95
	v_exp_f32_e32 v179, v96
	v_exp_f32_e32 v254, v97
	v_add_f32_e32 v219, v0, v219
	v_add_f32_e32 v219, v177, v219
	v_cvt_pk_fp8_f32 v249, v0, v177
	v_add_f32_e32 v219, v179, v219
	v_add_f32_e32 v219, v254, v219
	v_cvt_pk_fp8_f32 v249, v179, v254 op_sel:[0,0,1]
	ds_read_b128 v[90:93], v185 offset:32768
	ds_read_b128 v[94:97], v186 offset:32768
	s_waitcnt lgkmcnt(4)
	v_mfma_scale_f32_32x32x64_f8f6f4 v[114:129], v[82:89], v[138:145], v[114:129], v194, v193 op_sel_hi:[0,0,0]
	v_exp_f32_e32 v0, v66
	v_exp_f32_e32 v177, v67
	v_exp_f32_e32 v179, v68
	v_exp_f32_e32 v254, v69
	v_add_f32_e32 v219, v0, v219
	v_add_f32_e32 v219, v177, v219
	v_cvt_pk_fp8_f32 v250, v0, v177
	v_add_f32_e32 v219, v179, v219
	v_add_f32_e32 v219, v254, v219
	v_cvt_pk_fp8_f32 v250, v179, v254 op_sel:[0,0,1]
	s_waitcnt lgkmcnt(2)
	v_mfma_scale_f32_32x32x64_f8f6f4 v[98:113], v[222:229], v[138:145], v[98:113], v194, v193 op_sel_hi:[0,0,0]
	ds_read_b128 v[222:225], v185 offset:34816
	ds_read_b128 v[226:229], v186 offset:34816
	v_exp_f32_e32 v0, v70
	v_exp_f32_e32 v177, v71
	v_exp_f32_e32 v179, v72
	v_exp_f32_e32 v254, v73
	v_add_f32_e32 v219, v0, v219
	v_add_f32_e32 v219, v177, v219
	v_cvt_pk_fp8_f32 v251, v0, v177
	v_add_f32_e32 v219, v179, v219
	v_add_f32_e32 v219, v254, v219
	v_cvt_pk_fp8_f32 v251, v179, v254 op_sel:[0,0,1]
	v_exp_f32_e32 v0, v74
	v_exp_f32_e32 v177, v75
	v_exp_f32_e32 v179, v76
	v_exp_f32_e32 v254, v77
	v_add_f32_e32 v219, v0, v219
	v_add_f32_e32 v219, v177, v219
	v_cvt_pk_fp8_f32 v252, v0, v177
	v_add_f32_e32 v219, v179, v219
	v_add_f32_e32 v219, v254, v219
	v_cvt_pk_fp8_f32 v252, v179, v254 op_sel:[0,0,1]
	s_waitcnt lgkmcnt(2)
	v_mfma_scale_f32_32x32x64_f8f6f4 v[114:129], v[90:97], v[130:137], v[114:129], v194, v193 op_sel_hi:[0,0,0]
	v_exp_f32_e32 v0, v78
	v_exp_f32_e32 v177, v79
	v_exp_f32_e32 v179, v80
	v_exp_f32_e32 v254, v81
	v_add_f32_e32 v219, v0, v219
	v_add_f32_e32 v219, v177, v219
	v_cvt_pk_fp8_f32 v253, v0, v177
	v_add_f32_e32 v219, v179, v219
	v_add_f32_e32 v219, v254, v219
	v_cvt_pk_fp8_f32 v253, v179, v254 op_sel:[0,0,1]
	ds_read_b128 v[90:93], v185 offset:43008
	ds_read_b128 v[94:97], v186 offset:43008
	ds_read_b128 v[82:85], v185 offset:45056
	ds_read_b128 v[86:89], v186 offset:45056
	ds_read_b128 v[74:77], v185 offset:47104
	ds_read_b128 v[78:81], v186 offset:47104
	ds_read_b128 v[66:69], v185 offset:49152
	ds_read_b128 v[70:73], v186 offset:49152
	s_waitcnt lgkmcnt(8)
	v_mfma_scale_f32_32x32x64_f8f6f4 v[98:113], v[222:229], v[130:137], v[98:113], v194, v193 op_sel_hi:[0,0,0]
	v_mov_b32_e32 v0, v219
	s_nop 1
	v_permlane32_swap_b32_e32 v219, v0
	v_add_f32_e32 v219, v219, v0
	v_add_f32_e32 v209, v209, v219
	v_max_f32_e32 v177, v114, v115
	v_max3_f32 v177, v177, v116, v117
	v_max3_f32 v177, v177, v118, v119
	v_max3_f32 v177, v177, v120, v121
	v_max3_f32 v177, v177, v122, v123
	v_max3_f32 v177, v177, v124, v125
	v_max3_f32 v177, v177, v126, v127
	v_max3_f32 v177, v177, v128, v129
	s_waitcnt lgkmcnt(6)
	v_mfma_scale_f32_32x32x64_f8f6f4 v[50:65], v[246:253], v[90:97], v[50:65], v194, v194 op_sel_hi:[0,0,0]
	s_waitcnt vmcnt(0)
	ds_write_b128 v210, v[158:161] offset:8192
	ds_write_b128 v211, v[162:165] offset:24576
	s_waitcnt lgkmcnt(6)
	v_mfma_scale_f32_32x32x64_f8f6f4 v[34:49], v[246:253], v[82:89], v[34:49], v194, v194 op_sel_hi:[0,0,0]
	s_waitcnt lgkmcnt(0)
	s_barrier
	s_waitcnt lgkmcnt(2)
	v_mfma_scale_f32_32x32x64_f8f6f4 v[18:33], v[246:253], v[74:81], v[18:33], v194, v194 op_sel_hi:[0,0,0]
	global_load_dwordx4 v[158:161], v176, s[18:19]
	global_load_dwordx4 v[162:165], v178, s[16:17]
	v_add_u32_e32 v176, 0x2000, v176
	v_add_u32_e32 v178, 0x20000, v178
	s_waitcnt lgkmcnt(0)
	v_mfma_scale_f32_32x32x64_f8f6f4 v[2:17], v[246:253], v[66:73], v[2:17], v194, v194 op_sel_hi:[0,0,0]
	v_max_f32_e32 v0, v98, v99
	v_max3_f32 v0, v0, v100, v101
	v_max3_f32 v0, v0, v102, v103
	v_max3_f32 v0, v0, v104, v105
	v_max3_f32 v0, v0, v106, v107
	v_max3_f32 v0, v0, v108, v109
	v_max3_f32 v0, v0, v110, v111
	v_max3_f32 v0, v0, v112, v113
	v_max_f32_e32 v177, v177, v0
	v_mov_b32_e32 v0, v177
	s_nop 1
	v_permlane32_swap_b32_e32 v177, v0
	v_max_f32_e32 v177, v177, v0
	v_cmp_ge_f32_e32 vcc, s90, v177
	s_cmp_eq_u64 vcc, exec
	s_cbranch_scc0 .Lmla_s2_newmax
; __device__ __forceinline__ void finishSM9(f32x16& p0, f32x16& p1, float alpha, float& l_reg, v8i32& p8) {
; #pragma unroll
;   for (int r = 0; r < 16; ++r) { p0[r] = __builtin_amdgcn_exp2f(p0[r]); p1[r] = __builtin_amdgcn_exp2f(p1[r]); }
;   float ps = 0;
; #pragma unroll
;   for (int r = 0; r < 16; ++r) ps += p0[r];
; #pragma unroll
;   for (int r = 0; r < 16; ++r) ps += p1[r];
;   { auto rr = __builtin_amdgcn_permlane32_swap(__float_as_uint(ps), __float_as_uint(ps), false, false);
;     ps = __uint_as_float(rr[0]) + __uint_as_float(rr[1]); }
;   l_reg = l_reg * alpha + ps;
; #pragma unroll
;   for (int g = 0; g < 4; ++g) {
;     int w = __builtin_amdgcn_cvt_pk_fp8_f32(p0[4 * g], p0[4 * g + 1], 0, false); p8[g] = __builtin_amdgcn_cvt_pk_fp8_f32(p0[4 * g + 2], p0[4 * g + 3], w, true);
;     int u = __builtin_amdgcn_cvt_pk_fp8_f32(p1[4 * g], p1[4 * g + 1], 0, false); p8[4 + g] = __builtin_amdgcn_cvt_pk_fp8_f32(p1[4 * g + 2], p1[4 * g + 3], u, true); }
; }
; __device__ __forceinline__ void pv8(f32x16* o, const char* Vt, const v8i32 p8, int r32, int hi) {
;   const int sw = (r32 >> 2) & 3, a0 = r32 * 64 + (((hi * 2) ^ sw) << 4), a1 = r32 * 64 + (((hi * 2 + 1) ^ sw) << 4);
; #pragma unroll
;   for (int d0 = 0; d0 < 4; ++d0) {
;     const v8i32 vf = cat8(*reinterpret_cast<const v4i32*>(Vt + d0 * 2048 + a0), *reinterpret_cast<const v4i32*>(Vt + d0 * 2048 + a1));
;     o[d0] = __builtin_amdgcn_mfma_scale_f32_32x32x64_f8f6f4(p8, vf, o[d0], 0, 0, 0, 127, 0, 127); }
; }
; __device__ __forceinline__ void qkt9(f32x16& p0, f32x16& p1, const char* Kn, const char* Kr, const v8i32* qf, const float init, int r32, int hi) {
; #pragma unroll
;   for (int r = 0; r < 16; ++r) { p0[r] = init; p1[r] = init; }
; #pragma unroll
;   for (int s = 0; s < 2; ++s) { const int c0 = s * 4 + hi * 2;
;     const v8i32 a0 = cat8(*reinterpret_cast<const v4i32*>(Kn + KN8SW(r32, c0)), *reinterpret_cast<const v4i32*>(Kn + KN8SW(r32, c0 + 1)));
;     const v8i32 a1 = cat8(*reinterpret_cast<const v4i32*>(Kn + 4096 + KN8SW(r32, c0)), *reinterpret_cast<const v4i32*>(Kn + 4096 + KN8SW(r32, c0 + 1)));
;     p0 = __builtin_amdgcn_mfma_scale_f32_32x32x64_f8f6f4(a0, qf[s], p0, 0, 0, 0, 127, 0, 124);
;     p1 = __builtin_amdgcn_mfma_scale_f32_32x32x64_f8f6f4(a1, qf[s], p1, 0, 0, 0, 127, 0, 124); }
;   { const int c0 = hi * 2;
.Lmla_s2_cont:
	ds_read_b128 v[82:85], v215 offset:24576
	ds_read_b128 v[86:89], v216 offset:24576
	ds_read_b128 v[222:225], v215 offset:28672
	ds_read_b128 v[226:229], v216 offset:28672
	v_exp_f32_e32 v0, v114
	v_exp_f32_e32 v177, v115
	v_exp_f32_e32 v179, v116
	v_exp_f32_e32 v254, v117
	v_add_f32_e32 v219, v0, v177
	v_cvt_pk_fp8_f32 v246, v0, v177
	v_add_f32_e32 v219, v179, v219
	v_add_f32_e32 v219, v254, v219
	v_cvt_pk_fp8_f32 v246, v179, v254 op_sel:[0,0,1]
	s_waitcnt lgkmcnt(2)
	v_mfma_scale_f32_32x32x64_f8f6f4 v[82:97], v[82:89], v[146:153], v[230:245], v194, v193 op_sel_hi:[0,0,0]
	v_exp_f32_e32 v0, v118
	v_exp_f32_e32 v177, v119
	v_exp_f32_e32 v179, v120
	v_exp_f32_e32 v254, v121
	v_add_f32_e32 v219, v0, v219
	v_add_f32_e32 v219, v177, v219
	v_cvt_pk_fp8_f32 v247, v0, v177
	v_add_f32_e32 v219, v179, v219
	v_add_f32_e32 v219, v254, v219
	v_cvt_pk_fp8_f32 v247, v179, v254 op_sel:[0,0,1]
	ds_read_b128 v[114:117], v213 offset:24576
	ds_read_b128 v[118:121], v214 offset:24576
	s_waitcnt lgkmcnt(2)
	v_mfma_scale_f32_32x32x64_f8f6f4 v[66:81], v[222:229], v[146:153], v[230:245], v194, v193 op_sel_hi:[0,0,0]
	ds_read_b128 v[222:225], v213 offset:28672
	ds_read_b128 v[226:229], v214 offset:28672
	v_exp_f32_e32 v0, v122
	v_exp_f32_e32 v177, v123
	v_exp_f32_e32 v179, v124
	v_exp_f32_e32 v254, v125
	v_add_f32_e32 v219, v0, v219
	v_add_f32_e32 v219, v177, v219
	v_cvt_pk_fp8_f32 v248, v0, v177
	v_add_f32_e32 v219, v179, v219
	v_add_f32_e32 v219, v254, v219
	v_cvt_pk_fp8_f32 v248, v179, v254 op_sel:[0,0,1]
	v_exp_f32_e32 v0, v126
	v_exp_f32_e32 v177, v127
	v_exp_f32_e32 v179, v128
	v_exp_f32_e32 v254, v129
	v_add_f32_e32 v219, v0, v219
	v_add_f32_e32 v219, v177, v219
	v_cvt_pk_fp8_f32 v249, v0, v177
	v_add_f32_e32 v219, v179, v219
	v_add_f32_e32 v219, v254, v219
	v_cvt_pk_fp8_f32 v249, v179, v254 op_sel:[0,0,1]
	ds_read_b128 v[122:125], v185 offset:36864
	ds_read_b128 v[126:129], v186 offset:36864
	s_waitcnt lgkmcnt(4)
	v_mfma_scale_f32_32x32x64_f8f6f4 v[82:97], v[114:121], v[138:145], v[82:97], v194, v193 op_sel_hi:[0,0,0]
	v_exp_f32_e32 v0, v98
	v_exp_f32_e32 v177, v99
	v_exp_f32_e32 v179, v100
	v_exp_f32_e32 v254, v101
	v_add_f32_e32 v219, v0, v219
	v_add_f32_e32 v219, v177, v219
	v_cvt_pk_fp8_f32 v250, v0, v177
	v_add_f32_e32 v219, v179, v219
	v_add_f32_e32 v219, v254, v219
	v_cvt_pk_fp8_f32 v250, v179, v254 op_sel:[0,0,1]
	s_waitcnt lgkmcnt(2)
	v_mfma_scale_f32_32x32x64_f8f6f4 v[66:81], v[222:229], v[138:145], v[66:81], v194, v193 op_sel_hi:[0,0,0]
	ds_read_b128 v[222:225], v185 offset:38912
	ds_read_b128 v[226:229], v186 offset:38912
	v_exp_f32_e32 v0, v102
	v_exp_f32_e32 v177, v103
	v_exp_f32_e32 v179, v104
	v_exp_f32_e32 v254, v105
	v_add_f32_e32 v219, v0, v219
	v_add_f32_e32 v219, v177, v219
	v_cvt_pk_fp8_f32 v251, v0, v177
	v_add_f32_e32 v219, v179, v219
	v_add_f32_e32 v219, v254, v219
	v_cvt_pk_fp8_f32 v251, v179, v254 op_sel:[0,0,1]
	v_exp_f32_e32 v0, v106
	v_exp_f32_e32 v177, v107
	v_exp_f32_e32 v179, v108
	v_exp_f32_e32 v254, v109
	v_add_f32_e32 v219, v0, v219
	v_add_f32_e32 v219, v177, v219
	v_cvt_pk_fp8_f32 v252, v0, v177
	v_add_f32_e32 v219, v179, v219
	v_add_f32_e32 v219, v254, v219
	v_cvt_pk_fp8_f32 v252, v179, v254 op_sel:[0,0,1]
	s_waitcnt lgkmcnt(2)
	v_mfma_scale_f32_32x32x64_f8f6f4 v[82:97], v[122:129], v[130:137], v[82:97], v194, v193 op_sel_hi:[0,0,0]
	v_exp_f32_e32 v0, v110
	v_exp_f32_e32 v177, v111
	v_exp_f32_e32 v179, v112
	v_exp_f32_e32 v254, v113
	v_add_f32_e32 v219, v0, v219
	v_add_f32_e32 v219, v177, v219
	v_cvt_pk_fp8_f32 v253, v0, v177
	v_add_f32_e32 v219, v179, v219
	v_add_f32_e32 v219, v254, v219
	v_cvt_pk_fp8_f32 v253, v179, v254 op_sel:[0,0,1]
	ds_read_b128 v[122:125], v185 offset:0
	ds_read_b128 v[126:129], v186 offset:0
	ds_read_b128 v[114:117], v185 offset:2048
	ds_read_b128 v[118:121], v186 offset:2048
	ds_read_b128 v[106:109], v185 offset:4096
	ds_read_b128 v[110:113], v186 offset:4096
	ds_read_b128 v[98:101], v185 offset:6144
	ds_read_b128 v[102:105], v186 offset:6144
	s_waitcnt lgkmcnt(8)
	v_mfma_scale_f32_32x32x64_f8f6f4 v[66:81], v[222:229], v[130:137], v[66:81], v194, v193 op_sel_hi:[0,0,0]
	v_mov_b32_e32 v0, v219
	s_nop 1
	v_permlane32_swap_b32_e32 v219, v0
	v_add_f32_e32 v219, v219, v0
	v_add_f32_e32 v209, v209, v219
	v_max_f32_e32 v177, v82, v83
	v_max3_f32 v177, v177, v84, v85
	v_max3_f32 v177, v177, v86, v87
	v_max3_f32 v177, v177, v88, v89
	v_max3_f32 v177, v177, v90, v91
	v_max3_f32 v177, v177, v92, v93
	v_max3_f32 v177, v177, v94, v95
	v_max3_f32 v177, v177, v96, v97
	s_waitcnt lgkmcnt(6)
	v_mfma_scale_f32_32x32x64_f8f6f4 v[50:65], v[246:253], v[122:129], v[50:65], v194, v194 op_sel_hi:[0,0,0]
	s_waitcnt vmcnt(0)
	ds_write_b128 v210, v[158:161] offset:43008
	ds_write_b128 v211, v[162:165] offset:51200
	s_waitcnt lgkmcnt(6)
	v_mfma_scale_f32_32x32x64_f8f6f4 v[34:49], v[246:253], v[114:121], v[34:49], v194, v194 op_sel_hi:[0,0,0]
	s_waitcnt lgkmcnt(0)
	s_barrier
	s_waitcnt lgkmcnt(2)
	v_mfma_scale_f32_32x32x64_f8f6f4 v[18:33], v[246:253], v[106:113], v[18:33], v194, v194 op_sel_hi:[0,0,0]
	global_load_dwordx4 v[158:161], v176, s[18:19]
	global_load_dwordx4 v[162:165], v178, s[16:17]
	v_add_u32_e32 v176, 0x2000, v176
	v_add_u32_e32 v178, 0x20000, v178
	s_waitcnt lgkmcnt(0)
	v_mfma_scale_f32_32x32x64_f8f6f4 v[2:17], v[246:253], v[98:105], v[2:17], v194, v194 op_sel_hi:[0,0,0]
	v_max_f32_e32 v0, v66, v67
	v_max3_f32 v0, v0, v68, v69
	v_max3_f32 v0, v0, v70, v71
	v_max3_f32 v0, v0, v72, v73
	v_max3_f32 v0, v0, v74, v75
	v_max3_f32 v0, v0, v76, v77
	v_max3_f32 v0, v0, v78, v79
	v_max3_f32 v0, v0, v80, v81
	v_max_f32_e32 v177, v177, v0
	v_mov_b32_e32 v0, v177
	s_nop 1
	v_permlane32_swap_b32_e32 v177, v0
	v_max_f32_e32 v177, v177, v0
	v_cmp_ge_f32_e32 vcc, s90, v177
	s_cmp_eq_u64 vcc, exec
	s_cbranch_scc0 .Lmla_s3_newmax
; __device__ __forceinline__ void finishSM9(f32x16& p0, f32x16& p1, float alpha, float& l_reg, v8i32& p8) {
; #pragma unroll
;   for (int r = 0; r < 16; ++r) { p0[r] = __builtin_amdgcn_exp2f(p0[r]); p1[r] = __builtin_amdgcn_exp2f(p1[r]); }
;   float ps = 0;
; #pragma unroll
;   for (int r = 0; r < 16; ++r) ps += p0[r];
; #pragma unroll
;   for (int r = 0; r < 16; ++r) ps += p1[r];
;   { auto rr = __builtin_amdgcn_permlane32_swap(__float_as_uint(ps), __float_as_uint(ps), false, false);
;     ps = __uint_as_float(rr[0]) + __uint_as_float(rr[1]); }
;   l_reg = l_reg * alpha + ps;
; #pragma unroll
;   for (int g = 0; g < 4; ++g) {
;     int w = __builtin_amdgcn_cvt_pk_fp8_f32(p0[4 * g], p0[4 * g + 1], 0, false); p8[g] = __builtin_amdgcn_cvt_pk_fp8_f32(p0[4 * g + 2], p0[4 * g + 3], w, true);
;     int u = __builtin_amdgcn_cvt_pk_fp8_f32(p1[4 * g], p1[4 * g + 1], 0, false); p8[4 + g] = __builtin_amdgcn_cvt_pk_fp8_f32(p1[4 * g + 2], p1[4 * g + 3], u, true); }
; }
; __device__ __forceinline__ void pv8(f32x16* o, const char* Vt, const v8i32 p8, int r32, int hi) {
;   const int sw = (r32 >> 2) & 3, a0 = r32 * 64 + (((hi * 2) ^ sw) << 4), a1 = r32 * 64 + (((hi * 2 + 1) ^ sw) << 4);
; #pragma unroll
;   for (int d0 = 0; d0 < 4; ++d0) {
;     const v8i32 vf = cat8(*reinterpret_cast<const v4i32*>(Vt + d0 * 2048 + a0), *reinterpret_cast<const v4i32*>(Vt + d0 * 2048 + a1));
;     o[d0] = __builtin_amdgcn_mfma_scale_f32_32x32x64_f8f6f4(p8, vf, o[d0], 0, 0, 0, 127, 0, 127); }
; }
; __device__ __forceinline__ void qkt9(f32x16& p0, f32x16& p1, const char* Kn, const char* Kr, const v8i32* qf, const float init, int r32, int hi) {
; #pragma unroll
;   for (int r = 0; r < 16; ++r) { p0[r] = init; p1[r] = init; }
; #pragma unroll
;   for (int s = 0; s < 2; ++s) { const int c0 = s * 4 + hi * 2;
;     const v8i32 a0 = cat8(*reinterpret_cast<const v4i32*>(Kn + KN8SW(r32, c0)), *reinterpret_cast<const v4i32*>(Kn + KN8SW(r32, c0 + 1)));
;     const v8i32 a1 = cat8(*reinterpret_cast<const v4i32*>(Kn + 4096 + KN8SW(r32, c0)), *reinterpret_cast<const v4i32*>(Kn + 4096 + KN8SW(r32, c0 + 1)));
;     p0 = __builtin_amdgcn_mfma_scale_f32_32x32x64_f8f6f4(a0, qf[s], p0, 0, 0, 0, 127, 0, 124);
;     p1 = __builtin_amdgcn_mfma_scale_f32_32x32x64_f8f6f4(a1, qf[s], p1, 0, 0, 0, 127, 0, 124); }
;   { const int c0 = hi * 2;
.Lmla_s3_cont:
	ds_read_b128 v[114:117], v215 offset:51200
	ds_read_b128 v[118:121], v216 offset:51200
	ds_read_b128 v[222:225], v215 offset:55296
	ds_read_b128 v[226:229], v216 offset:55296
	v_exp_f32_e32 v0, v82
	v_exp_f32_e32 v177, v83
	v_exp_f32_e32 v179, v84
	v_exp_f32_e32 v254, v85
	v_add_f32_e32 v219, v0, v177
	v_cvt_pk_fp8_f32 v246, v0, v177
	v_add_f32_e32 v219, v179, v219
	v_add_f32_e32 v219, v254, v219
	v_cvt_pk_fp8_f32 v246, v179, v254 op_sel:[0,0,1]
	s_waitcnt lgkmcnt(2)
	v_mfma_scale_f32_32x32x64_f8f6f4 v[114:129], v[114:121], v[146:153], v[230:245], v194, v193 op_sel_hi:[0,0,0]
	v_exp_f32_e32 v0, v86
	v_exp_f32_e32 v177, v87
	v_exp_f32_e32 v179, v88
	v_exp_f32_e32 v254, v89
	v_add_f32_e32 v219, v0, v219
	v_add_f32_e32 v219, v177, v219
	v_cvt_pk_fp8_f32 v247, v0, v177
	v_add_f32_e32 v219, v179, v219
	v_add_f32_e32 v219, v254, v219
	v_cvt_pk_fp8_f32 v247, v179, v254 op_sel:[0,0,1]
	ds_read_b128 v[82:85], v213 offset:51200
	ds_read_b128 v[86:89], v214 offset:51200
	s_waitcnt lgkmcnt(2)
	v_mfma_scale_f32_32x32x64_f8f6f4 v[98:113], v[222:229], v[146:153], v[230:245], v194, v193 op_sel_hi:[0,0,0]
	ds_read_b128 v[222:225], v213 offset:55296
	ds_read_b128 v[226:229], v214 offset:55296
	v_exp_f32_e32 v0, v90
	v_exp_f32_e32 v177, v91
	v_exp_f32_e32 v179, v92
	v_exp_f32_e32 v254, v93
	v_add_f32_e32 v219, v0, v219
	v_add_f32_e32 v219, v177, v219
	v_cvt_pk_fp8_f32 v248, v0, v177
	v_add_f32_e32 v219, v179, v219
	v_add_f32_e32 v219, v254, v219
	v_cvt_pk_fp8_f32 v248, v179, v254 op_sel:[0,0,1]
	v_exp_f32_e32 v0, v94
	v_exp_f32_e32 v177, v95
	v_exp_f32_e32 v179, v96
	v_exp_f32_e32 v254, v97
	v_add_f32_e32 v219, v0, v219
	v_add_f32_e32 v219, v177, v219
	v_cvt_pk_fp8_f32 v249, v0, v177
	v_add_f32_e32 v219, v179, v219
	v_add_f32_e32 v219, v254, v219
	v_cvt_pk_fp8_f32 v249, v179, v254 op_sel:[0,0,1]
	ds_read_b128 v[90:93], v185 offset:59392
	ds_read_b128 v[94:97], v186 offset:59392
	s_waitcnt lgkmcnt(4)
	v_mfma_scale_f32_32x32x64_f8f6f4 v[114:129], v[82:89], v[138:145], v[114:129], v194, v193 op_sel_hi:[0,0,0]
	v_exp_f32_e32 v0, v66
	v_exp_f32_e32 v177, v67
	v_exp_f32_e32 v179, v68
	v_exp_f32_e32 v254, v69
	v_add_f32_e32 v219, v0, v219
	v_add_f32_e32 v219, v177, v219
	v_cvt_pk_fp8_f32 v250, v0, v177
	v_add_f32_e32 v219, v179, v219
	v_add_f32_e32 v219, v254, v219
	v_cvt_pk_fp8_f32 v250, v179, v254 op_sel:[0,0,1]
	s_waitcnt lgkmcnt(2)
	v_mfma_scale_f32_32x32x64_f8f6f4 v[98:113], v[222:229], v[138:145], v[98:113], v194, v193 op_sel_hi:[0,0,0]
	ds_read_b128 v[222:225], v185 offset:61440
	ds_read_b128 v[226:229], v186 offset:61440
	v_exp_f32_e32 v0, v70
	v_exp_f32_e32 v177, v71
	v_exp_f32_e32 v179, v72
	v_exp_f32_e32 v254, v73
	v_add_f32_e32 v219, v0, v219
	v_add_f32_e32 v219, v177, v219
	v_cvt_pk_fp8_f32 v251, v0, v177
	v_add_f32_e32 v219, v179, v219
	v_add_f32_e32 v219, v254, v219
	v_cvt_pk_fp8_f32 v251, v179, v254 op_sel:[0,0,1]
	v_exp_f32_e32 v0, v74
	v_exp_f32_e32 v177, v75
	v_exp_f32_e32 v179, v76
	v_exp_f32_e32 v254, v77
	v_add_f32_e32 v219, v0, v219
	v_add_f32_e32 v219, v177, v219
	v_cvt_pk_fp8_f32 v252, v0, v177
	v_add_f32_e32 v219, v179, v219
	v_add_f32_e32 v219, v254, v219
	v_cvt_pk_fp8_f32 v252, v179, v254 op_sel:[0,0,1]
	s_waitcnt lgkmcnt(2)
	v_mfma_scale_f32_32x32x64_f8f6f4 v[114:129], v[90:97], v[130:137], v[114:129], v194, v193 op_sel_hi:[0,0,0]
	v_exp_f32_e32 v0, v78
	v_exp_f32_e32 v177, v79
	v_exp_f32_e32 v179, v80
	v_exp_f32_e32 v254, v81
	v_add_f32_e32 v219, v0, v219
	v_add_f32_e32 v219, v177, v219
	v_cvt_pk_fp8_f32 v253, v0, v177
	v_add_f32_e32 v219, v179, v219
	v_add_f32_e32 v219, v254, v219
	v_cvt_pk_fp8_f32 v253, v179, v254 op_sel:[0,0,1]
	ds_read_b128 v[90:93], v185 offset:8192
	ds_read_b128 v[94:97], v186 offset:8192
	ds_read_b128 v[82:85], v185 offset:10240
	ds_read_b128 v[86:89], v186 offset:10240
	ds_read_b128 v[74:77], v185 offset:12288
	ds_read_b128 v[78:81], v186 offset:12288
	ds_read_b128 v[66:69], v185 offset:14336
	ds_read_b128 v[70:73], v186 offset:14336
	s_waitcnt lgkmcnt(8)
	v_mfma_scale_f32_32x32x64_f8f6f4 v[98:113], v[222:229], v[130:137], v[98:113], v194, v193 op_sel_hi:[0,0,0]
	v_mov_b32_e32 v0, v219
	s_nop 1
	v_permlane32_swap_b32_e32 v219, v0
	v_add_f32_e32 v219, v219, v0
	v_add_f32_e32 v209, v209, v219
	v_max_f32_e32 v177, v114, v115
	v_max3_f32 v177, v177, v116, v117
	v_max3_f32 v177, v177, v118, v119
	v_max3_f32 v177, v177, v120, v121
	v_max3_f32 v177, v177, v122, v123
	v_max3_f32 v177, v177, v124, v125
	v_max3_f32 v177, v177, v126, v127
	v_max3_f32 v177, v177, v128, v129
	s_waitcnt lgkmcnt(6)
	v_mfma_scale_f32_32x32x64_f8f6f4 v[50:65], v[246:253], v[90:97], v[50:65], v194, v194 op_sel_hi:[0,0,0]
	s_waitcnt vmcnt(0)
	ds_write_b128 v210, v[158:161]
	ds_write_b128 v211, v[162:165] offset:16384
	s_waitcnt lgkmcnt(6)
	v_mfma_scale_f32_32x32x64_f8f6f4 v[34:49], v[246:253], v[82:89], v[34:49], v194, v194 op_sel_hi:[0,0,0]
	s_waitcnt lgkmcnt(0)
	s_barrier
	s_waitcnt lgkmcnt(2)
	v_mfma_scale_f32_32x32x64_f8f6f4 v[18:33], v[246:253], v[74:81], v[18:33], v194, v194 op_sel_hi:[0,0,0]
	global_load_dwordx4 v[158:161], v176, s[18:19]
	global_load_dwordx4 v[162:165], v178, s[16:17]
	v_add_u32_e32 v176, 0x2000, v176
	v_add_u32_e32 v178, 0x20000, v178
	s_waitcnt lgkmcnt(0)
	v_mfma_scale_f32_32x32x64_f8f6f4 v[2:17], v[246:253], v[66:73], v[2:17], v194, v194 op_sel_hi:[0,0,0]
	v_max_f32_e32 v0, v98, v99
	v_max3_f32 v0, v0, v100, v101
	v_max3_f32 v0, v0, v102, v103
	v_max3_f32 v0, v0, v104, v105
	v_max3_f32 v0, v0, v106, v107
	v_max3_f32 v0, v0, v108, v109
	v_max3_f32 v0, v0, v110, v111
	v_max3_f32 v0, v0, v112, v113
	v_max_f32_e32 v177, v177, v0
	v_mov_b32_e32 v0, v177
	s_nop 1
	v_permlane32_swap_b32_e32 v177, v0
	v_max_f32_e32 v177, v177, v0
	v_cmp_ge_f32_e32 vcc, s90, v177
	s_cmp_eq_u64 vcc, exec
	s_cbranch_scc0 .Lmla_s4_newmax
; __device__ __forceinline__ void finishSM9(f32x16& p0, f32x16& p1, float alpha, float& l_reg, v8i32& p8) {
; #pragma unroll
;   for (int r = 0; r < 16; ++r) { p0[r] = __builtin_amdgcn_exp2f(p0[r]); p1[r] = __builtin_amdgcn_exp2f(p1[r]); }
;   float ps = 0;
; #pragma unroll
;   for (int r = 0; r < 16; ++r) ps += p0[r];
; #pragma unroll
;   for (int r = 0; r < 16; ++r) ps += p1[r];
;   { auto rr = __builtin_amdgcn_permlane32_swap(__float_as_uint(ps), __float_as_uint(ps), false, false);
;     ps = __uint_as_float(rr[0]) + __uint_as_float(rr[1]); }
;   l_reg = l_reg * alpha + ps;
; #pragma unroll
;   for (int g = 0; g < 4; ++g) {
;     int w = __builtin_amdgcn_cvt_pk_fp8_f32(p0[4 * g], p0[4 * g + 1], 0, false); p8[g] = __builtin_amdgcn_cvt_pk_fp8_f32(p0[4 * g + 2], p0[4 * g + 3], w, true);
;     int u = __builtin_amdgcn_cvt_pk_fp8_f32(p1[4 * g], p1[4 * g + 1], 0, false); p8[4 + g] = __builtin_amdgcn_cvt_pk_fp8_f32(p1[4 * g + 2], p1[4 * g + 3], u, true); }
; }
; __device__ __forceinline__ void pv8(f32x16* o, const char* Vt, const v8i32 p8, int r32, int hi) {
;   const int sw = (r32 >> 2) & 3, a0 = r32 * 64 + (((hi * 2) ^ sw) << 4), a1 = r32 * 64 + (((hi * 2 + 1) ^ sw) << 4);
; #pragma unroll
;   for (int d0 = 0; d0 < 4; ++d0) {
;     const v8i32 vf = cat8(*reinterpret_cast<const v4i32*>(Vt + d0 * 2048 + a0), *reinterpret_cast<const v4i32*>(Vt + d0 * 2048 + a1));
;     o[d0] = __builtin_amdgcn_mfma_scale_f32_32x32x64_f8f6f4(p8, vf, o[d0], 0, 0, 0, 127, 0, 127); }
; }
; __device__ __forceinline__ void qkt9(f32x16& p0, f32x16& p1, const char* Kn, const char* Kr, const v8i32* qf, const float init, int r32, int hi) {
; #pragma unroll
;   for (int r = 0; r < 16; ++r) { p0[r] = init; p1[r] = init; }
; #pragma unroll
;   for (int s = 0; s < 2; ++s) { const int c0 = s * 4 + hi * 2;
;     const v8i32 a0 = cat8(*reinterpret_cast<const v4i32*>(Kn + KN8SW(r32, c0)), *reinterpret_cast<const v4i32*>(Kn + KN8SW(r32, c0 + 1)));
;     const v8i32 a1 = cat8(*reinterpret_cast<const v4i32*>(Kn + 4096 + KN8SW(r32, c0)), *reinterpret_cast<const v4i32*>(Kn + 4096 + KN8SW(r32, c0 + 1)));
;     p0 = __builtin_amdgcn_mfma_scale_f32_32x32x64_f8f6f4(a0, qf[s], p0, 0, 0, 0, 127, 0, 124);
;     p1 = __builtin_amdgcn_mfma_scale_f32_32x32x64_f8f6f4(a1, qf[s], p1, 0, 0, 0, 127, 0, 124); }
;   { const int c0 = hi * 2;
.Lmla_s4_cont:
	ds_read_b128 v[82:85], v215 offset:16384
	ds_read_b128 v[86:89], v216 offset:16384
	ds_read_b128 v[222:225], v215 offset:20480
	ds_read_b128 v[226:229], v216 offset:20480
	v_exp_f32_e32 v0, v114
	v_exp_f32_e32 v177, v115
	v_exp_f32_e32 v179, v116
	v_exp_f32_e32 v254, v117
	v_add_f32_e32 v219, v0, v177
	v_cvt_pk_fp8_f32 v246, v0, v177
	v_add_f32_e32 v219, v179, v219
	v_add_f32_e32 v219, v254, v219
	v_cvt_pk_fp8_f32 v246, v179, v254 op_sel:[0,0,1]
	s_waitcnt lgkmcnt(2)
	v_mfma_scale_f32_32x32x64_f8f6f4 v[82:97], v[82:89], v[146:153], v[230:245], v194, v193 op_sel_hi:[0,0,0]
	v_exp_f32_e32 v0, v118
	v_exp_f32_e32 v177, v119
	v_exp_f32_e32 v179, v120
	v_exp_f32_e32 v254, v121
	v_add_f32_e32 v219, v0, v219
	v_add_f32_e32 v219, v177, v219
	v_cvt_pk_fp8_f32 v247, v0, v177
	v_add_f32_e32 v219, v179, v219
	v_add_f32_e32 v219, v254, v219
	v_cvt_pk_fp8_f32 v247, v179, v254 op_sel:[0,0,1]
	ds_read_b128 v[114:117], v213 offset:16384
	ds_read_b128 v[118:121], v214 offset:16384
	s_waitcnt lgkmcnt(2)
	v_mfma_scale_f32_32x32x64_f8f6f4 v[66:81], v[222:229], v[146:153], v[230:245], v194, v193 op_sel_hi:[0,0,0]
	ds_read_b128 v[222:225], v213 offset:20480
	ds_read_b128 v[226:229], v214 offset:20480
	v_exp_f32_e32 v0, v122
	v_exp_f32_e32 v177, v123
	v_exp_f32_e32 v179, v124
	v_exp_f32_e32 v254, v125
	v_add_f32_e32 v219, v0, v219
	v_add_f32_e32 v219, v177, v219
	v_cvt_pk_fp8_f32 v248, v0, v177
	v_add_f32_e32 v219, v179, v219
	v_add_f32_e32 v219, v254, v219
	v_cvt_pk_fp8_f32 v248, v179, v254 op_sel:[0,0,1]
	v_exp_f32_e32 v0, v126
	v_exp_f32_e32 v177, v127
	v_exp_f32_e32 v179, v128
	v_exp_f32_e32 v254, v129
	v_add_f32_e32 v219, v0, v219
	v_add_f32_e32 v219, v177, v219
	v_cvt_pk_fp8_f32 v249, v0, v177
	v_add_f32_e32 v219, v179, v219
	v_add_f32_e32 v219, v254, v219
	v_cvt_pk_fp8_f32 v249, v179, v254 op_sel:[0,0,1]
	ds_read_b128 v[122:125], v185 offset:32768
	ds_read_b128 v[126:129], v186 offset:32768
	s_waitcnt lgkmcnt(4)
	v_mfma_scale_f32_32x32x64_f8f6f4 v[82:97], v[114:121], v[138:145], v[82:97], v194, v193 op_sel_hi:[0,0,0]
	v_exp_f32_e32 v0, v98
	v_exp_f32_e32 v177, v99
	v_exp_f32_e32 v179, v100
	v_exp_f32_e32 v254, v101
	v_add_f32_e32 v219, v0, v219
	v_add_f32_e32 v219, v177, v219
	v_cvt_pk_fp8_f32 v250, v0, v177
	v_add_f32_e32 v219, v179, v219
	v_add_f32_e32 v219, v254, v219
	v_cvt_pk_fp8_f32 v250, v179, v254 op_sel:[0,0,1]
	s_waitcnt lgkmcnt(2)
	v_mfma_scale_f32_32x32x64_f8f6f4 v[66:81], v[222:229], v[138:145], v[66:81], v194, v193 op_sel_hi:[0,0,0]
	ds_read_b128 v[222:225], v185 offset:34816
	ds_read_b128 v[226:229], v186 offset:34816
	v_exp_f32_e32 v0, v102
	v_exp_f32_e32 v177, v103
	v_exp_f32_e32 v179, v104
	v_exp_f32_e32 v254, v105
	v_add_f32_e32 v219, v0, v219
	v_add_f32_e32 v219, v177, v219
	v_cvt_pk_fp8_f32 v251, v0, v177
	v_add_f32_e32 v219, v179, v219
	v_add_f32_e32 v219, v254, v219
	v_cvt_pk_fp8_f32 v251, v179, v254 op_sel:[0,0,1]
	v_exp_f32_e32 v0, v106
	v_exp_f32_e32 v177, v107
	v_exp_f32_e32 v179, v108
	v_exp_f32_e32 v254, v109
	v_add_f32_e32 v219, v0, v219
	v_add_f32_e32 v219, v177, v219
	v_cvt_pk_fp8_f32 v252, v0, v177
	v_add_f32_e32 v219, v179, v219
	v_add_f32_e32 v219, v254, v219
	v_cvt_pk_fp8_f32 v252, v179, v254 op_sel:[0,0,1]
	s_waitcnt lgkmcnt(2)
	v_mfma_scale_f32_32x32x64_f8f6f4 v[82:97], v[122:129], v[130:137], v[82:97], v194, v193 op_sel_hi:[0,0,0]
	v_exp_f32_e32 v0, v110
	v_exp_f32_e32 v177, v111
	v_exp_f32_e32 v179, v112
	v_exp_f32_e32 v254, v113
	v_add_f32_e32 v219, v0, v219
	v_add_f32_e32 v219, v177, v219
	v_cvt_pk_fp8_f32 v253, v0, v177
	v_add_f32_e32 v219, v179, v219
	v_add_f32_e32 v219, v254, v219
	v_cvt_pk_fp8_f32 v253, v179, v254 op_sel:[0,0,1]
	ds_read_b128 v[122:125], v185 offset:43008
	ds_read_b128 v[126:129], v186 offset:43008
	ds_read_b128 v[114:117], v185 offset:45056
	ds_read_b128 v[118:121], v186 offset:45056
	ds_read_b128 v[106:109], v185 offset:47104
	ds_read_b128 v[110:113], v186 offset:47104
	ds_read_b128 v[98:101], v185 offset:49152
	ds_read_b128 v[102:105], v186 offset:49152
	s_waitcnt lgkmcnt(8)
	v_mfma_scale_f32_32x32x64_f8f6f4 v[66:81], v[222:229], v[130:137], v[66:81], v194, v193 op_sel_hi:[0,0,0]
	v_mov_b32_e32 v0, v219
	s_nop 1
	v_permlane32_swap_b32_e32 v219, v0
	v_add_f32_e32 v219, v219, v0
	v_add_f32_e32 v209, v209, v219
	v_max_f32_e32 v177, v82, v83
	v_max3_f32 v177, v177, v84, v85
	v_max3_f32 v177, v177, v86, v87
	v_max3_f32 v177, v177, v88, v89
	v_max3_f32 v177, v177, v90, v91
	v_max3_f32 v177, v177, v92, v93
	v_max3_f32 v177, v177, v94, v95
	v_max3_f32 v177, v177, v96, v97
	s_waitcnt lgkmcnt(6)
	v_mfma_scale_f32_32x32x64_f8f6f4 v[50:65], v[246:253], v[122:129], v[50:65], v194, v194 op_sel_hi:[0,0,0]
	s_waitcnt vmcnt(0)
	ds_write_b128 v210, v[158:161] offset:8192
	ds_write_b128 v211, v[162:165] offset:24576
	s_waitcnt lgkmcnt(6)
	v_mfma_scale_f32_32x32x64_f8f6f4 v[34:49], v[246:253], v[114:121], v[34:49], v194, v194 op_sel_hi:[0,0,0]
	s_waitcnt lgkmcnt(0)
	s_barrier
	s_waitcnt lgkmcnt(2)
	v_mfma_scale_f32_32x32x64_f8f6f4 v[18:33], v[246:253], v[106:113], v[18:33], v194, v194 op_sel_hi:[0,0,0]
	global_load_dwordx4 v[158:161], v176, s[18:19]
	global_load_dwordx4 v[162:165], v178, s[16:17]
	v_add_u32_e32 v176, 0x2000, v176
	v_add_u32_e32 v178, 0x20000, v178
	s_waitcnt lgkmcnt(0)
	v_mfma_scale_f32_32x32x64_f8f6f4 v[2:17], v[246:253], v[98:105], v[2:17], v194, v194 op_sel_hi:[0,0,0]
	v_max_f32_e32 v0, v66, v67
	v_max3_f32 v0, v0, v68, v69
	v_max3_f32 v0, v0, v70, v71
	v_max3_f32 v0, v0, v72, v73
	v_max3_f32 v0, v0, v74, v75
	v_max3_f32 v0, v0, v76, v77
	v_max3_f32 v0, v0, v78, v79
	v_max3_f32 v0, v0, v80, v81
	v_max_f32_e32 v177, v177, v0
	v_mov_b32_e32 v0, v177
	s_nop 1
	v_permlane32_swap_b32_e32 v177, v0
	v_max_f32_e32 v177, v177, v0
	v_cmp_ge_f32_e32 vcc, s90, v177
	s_cmp_eq_u64 vcc, exec
	s_cbranch_scc0 .Lmla_s5_newmax
; __device__ __forceinline__ void finishSM9(f32x16& p0, f32x16& p1, float alpha, float& l_reg, v8i32& p8) {
; #pragma unroll
;   for (int r = 0; r < 16; ++r) { p0[r] = __builtin_amdgcn_exp2f(p0[r]); p1[r] = __builtin_amdgcn_exp2f(p1[r]); }
;   float ps = 0;
; #pragma unroll
;   for (int r = 0; r < 16; ++r) ps += p0[r];
; #pragma unroll
;   for (int r = 0; r < 16; ++r) ps += p1[r];
;   { auto rr = __builtin_amdgcn_permlane32_swap(__float_as_uint(ps), __float_as_uint(ps), false, false);
;     ps = __uint_as_float(rr[0]) + __uint_as_float(rr[1]); }
;   l_reg = l_reg * alpha + ps;
; #pragma unroll
;   for (int g = 0; g < 4; ++g) {
;     int w = __builtin_amdgcn_cvt_pk_fp8_f32(p0[4 * g], p0[4 * g + 1], 0, false); p8[g] = __builtin_amdgcn_cvt_pk_fp8_f32(p0[4 * g + 2], p0[4 * g + 3], w, true);
;     int u = __builtin_amdgcn_cvt_pk_fp8_f32(p1[4 * g], p1[4 * g + 1], 0, false); p8[4 + g] = __builtin_amdgcn_cvt_pk_fp8_f32(p1[4 * g + 2], p1[4 * g + 3], u, true); }
; }
; __device__ __forceinline__ void pv8(f32x16* o, const char* Vt, const v8i32 p8, int r32, int hi) {
;   const int sw = (r32 >> 2) & 3, a0 = r32 * 64 + (((hi * 2) ^ sw) << 4), a1 = r32 * 64 + (((hi * 2 + 1) ^ sw) << 4);
; #pragma unroll
;   for (int d0 = 0; d0 < 4; ++d0) {
;     const v8i32 vf = cat8(*reinterpret_cast<const v4i32*>(Vt + d0 * 2048 + a0), *reinterpret_cast<const v4i32*>(Vt + d0 * 2048 + a1));
;     o[d0] = __builtin_amdgcn_mfma_scale_f32_32x32x64_f8f6f4(p8, vf, o[d0], 0, 0, 0, 127, 0, 127); }
; }
; __device__ __forceinline__ void qkt9(f32x16& p0, f32x16& p1, const char* Kn, const char* Kr, const v8i32* qf, const float init, int r32, int hi) {
; #pragma unroll
;   for (int r = 0; r < 16; ++r) { p0[r] = init; p1[r] = init; }
; #pragma unroll
;   for (int s = 0; s < 2; ++s) { const int c0 = s * 4 + hi * 2;
;     const v8i32 a0 = cat8(*reinterpret_cast<const v4i32*>(Kn + KN8SW(r32, c0)), *reinterpret_cast<const v4i32*>(Kn + KN8SW(r32, c0 + 1)));
;     const v8i32 a1 = cat8(*reinterpret_cast<const v4i32*>(Kn + 4096 + KN8SW(r32, c0)), *reinterpret_cast<const v4i32*>(Kn + 4096 + KN8SW(r32, c0 + 1)));
;     p0 = __builtin_amdgcn_mfma_scale_f32_32x32x64_f8f6f4(a0, qf[s], p0, 0, 0, 0, 127, 0, 124);
;     p1 = __builtin_amdgcn_mfma_scale_f32_32x32x64_f8f6f4(a1, qf[s], p1, 0, 0, 0, 127, 0, 124); }
;   { const int c0 = hi * 2;
.Lmla_s5_cont:
	s_add_i32 s30, s30, 1
	s_cmpk_lt_u32 s30, 42
	s_cbranch_scc1 .Lmla_stag_loop
	ds_read_b128 v[114:117], v215 offset:24576
	ds_read_b128 v[118:121], v216 offset:24576
	ds_read_b128 v[222:225], v215 offset:28672
	ds_read_b128 v[226:229], v216 offset:28672
	v_exp_f32_e32 v0, v82
	v_exp_f32_e32 v177, v83
	v_exp_f32_e32 v179, v84
	v_exp_f32_e32 v254, v85
	v_add_f32_e32 v219, v0, v177
	v_cvt_pk_fp8_f32 v246, v0, v177
	v_add_f32_e32 v219, v179, v219
	v_add_f32_e32 v219, v254, v219
	v_cvt_pk_fp8_f32 v246, v179, v254 op_sel:[0,0,1]
	s_waitcnt lgkmcnt(2)
	v_mfma_scale_f32_32x32x64_f8f6f4 v[114:129], v[114:121], v[146:153], v[230:245], v194, v193 op_sel_hi:[0,0,0]
	v_exp_f32_e32 v0, v86
	v_exp_f32_e32 v177, v87
	v_exp_f32_e32 v179, v88
	v_exp_f32_e32 v254, v89
	v_add_f32_e32 v219, v0, v219
	v_add_f32_e32 v219, v177, v219
	v_cvt_pk_fp8_f32 v247, v0, v177
	v_add_f32_e32 v219, v179, v219
	v_add_f32_e32 v219, v254, v219
	v_cvt_pk_fp8_f32 v247, v179, v254 op_sel:[0,0,1]
	ds_read_b128 v[82:85], v213 offset:24576
	ds_read_b128 v[86:89], v214 offset:24576
	s_waitcnt lgkmcnt(2)
	v_mfma_scale_f32_32x32x64_f8f6f4 v[98:113], v[222:229], v[146:153], v[230:245], v194, v193 op_sel_hi:[0,0,0]
	ds_read_b128 v[222:225], v213 offset:28672
	ds_read_b128 v[226:229], v214 offset:28672
	v_exp_f32_e32 v0, v90
	v_exp_f32_e32 v177, v91
	v_exp_f32_e32 v179, v92
	v_exp_f32_e32 v254, v93
	v_add_f32_e32 v219, v0, v219
	v_add_f32_e32 v219, v177, v219
	v_cvt_pk_fp8_f32 v248, v0, v177
	v_add_f32_e32 v219, v179, v219
	v_add_f32_e32 v219, v254, v219
	v_cvt_pk_fp8_f32 v248, v179, v254 op_sel:[0,0,1]
	v_exp_f32_e32 v0, v94
	v_exp_f32_e32 v177, v95
	v_exp_f32_e32 v179, v96
	v_exp_f32_e32 v254, v97
	v_add_f32_e32 v219, v0, v219
	v_add_f32_e32 v219, v177, v219
	v_cvt_pk_fp8_f32 v249, v0, v177
	v_add_f32_e32 v219, v179, v219
	v_add_f32_e32 v219, v254, v219
	v_cvt_pk_fp8_f32 v249, v179, v254 op_sel:[0,0,1]
	ds_read_b128 v[90:93], v185 offset:36864
	ds_read_b128 v[94:97], v186 offset:36864
	s_waitcnt lgkmcnt(4)
	v_mfma_scale_f32_32x32x64_f8f6f4 v[114:129], v[82:89], v[138:145], v[114:129], v194, v193 op_sel_hi:[0,0,0]
	v_exp_f32_e32 v0, v66
	v_exp_f32_e32 v177, v67
	v_exp_f32_e32 v179, v68
	v_exp_f32_e32 v254, v69
	v_add_f32_e32 v219, v0, v219
	v_add_f32_e32 v219, v177, v219
	v_cvt_pk_fp8_f32 v250, v0, v177
	v_add_f32_e32 v219, v179, v219
	v_add_f32_e32 v219, v254, v219
	v_cvt_pk_fp8_f32 v250, v179, v254 op_sel:[0,0,1]
	s_waitcnt lgkmcnt(2)
	v_mfma_scale_f32_32x32x64_f8f6f4 v[98:113], v[222:229], v[138:145], v[98:113], v194, v193 op_sel_hi:[0,0,0]
	ds_read_b128 v[222:225], v185 offset:38912
	ds_read_b128 v[226:229], v186 offset:38912
	v_exp_f32_e32 v0, v70
	v_exp_f32_e32 v177, v71
	v_exp_f32_e32 v179, v72
	v_exp_f32_e32 v254, v73
	v_add_f32_e32 v219, v0, v219
	v_add_f32_e32 v219, v177, v219
	v_cvt_pk_fp8_f32 v251, v0, v177
	v_add_f32_e32 v219, v179, v219
	v_add_f32_e32 v219, v254, v219
	v_cvt_pk_fp8_f32 v251, v179, v254 op_sel:[0,0,1]
	v_exp_f32_e32 v0, v74
	v_exp_f32_e32 v177, v75
	v_exp_f32_e32 v179, v76
	v_exp_f32_e32 v254, v77
	v_add_f32_e32 v219, v0, v219
	v_add_f32_e32 v219, v177, v219
	v_cvt_pk_fp8_f32 v252, v0, v177
	v_add_f32_e32 v219, v179, v219
	v_add_f32_e32 v219, v254, v219
	v_cvt_pk_fp8_f32 v252, v179, v254 op_sel:[0,0,1]
	s_waitcnt lgkmcnt(2)
	v_mfma_scale_f32_32x32x64_f8f6f4 v[114:129], v[90:97], v[130:137], v[114:129], v194, v193 op_sel_hi:[0,0,0]
	v_exp_f32_e32 v0, v78
	v_exp_f32_e32 v177, v79
	v_exp_f32_e32 v179, v80
	v_exp_f32_e32 v254, v81
	v_add_f32_e32 v219, v0, v219
	v_add_f32_e32 v219, v177, v219
	v_cvt_pk_fp8_f32 v253, v0, v177
	v_add_f32_e32 v219, v179, v219
	v_add_f32_e32 v219, v254, v219
	v_cvt_pk_fp8_f32 v253, v179, v254 op_sel:[0,0,1]
	ds_read_b128 v[90:93], v185 offset:0
	ds_read_b128 v[94:97], v186 offset:0
	ds_read_b128 v[82:85], v185 offset:2048
	ds_read_b128 v[86:89], v186 offset:2048
	ds_read_b128 v[74:77], v185 offset:4096
	ds_read_b128 v[78:81], v186 offset:4096
	ds_read_b128 v[66:69], v185 offset:6144
	ds_read_b128 v[70:73], v186 offset:6144
	s_waitcnt lgkmcnt(8)
	v_mfma_scale_f32_32x32x64_f8f6f4 v[98:113], v[222:229], v[130:137], v[98:113], v194, v193 op_sel_hi:[0,0,0]
	v_mov_b32_e32 v0, v219
	s_nop 1
	v_permlane32_swap_b32_e32 v219, v0
	v_add_f32_e32 v219, v219, v0
	v_add_f32_e32 v209, v209, v219
	v_max_f32_e32 v177, v114, v115
	v_max3_f32 v177, v177, v116, v117
	v_max3_f32 v177, v177, v118, v119
	v_max3_f32 v177, v177, v120, v121
	v_max3_f32 v177, v177, v122, v123
	v_max3_f32 v177, v177, v124, v125
	v_max3_f32 v177, v177, v126, v127
	v_max3_f32 v177, v177, v128, v129
	s_waitcnt lgkmcnt(6)
	v_mfma_scale_f32_32x32x64_f8f6f4 v[50:65], v[246:253], v[90:97], v[50:65], v194, v194 op_sel_hi:[0,0,0]
	s_waitcnt vmcnt(0)
	ds_write_b128 v210, v[158:161] offset:43008
	ds_write_b128 v211, v[162:165] offset:51200
	s_waitcnt lgkmcnt(6)
	v_mfma_scale_f32_32x32x64_f8f6f4 v[34:49], v[246:253], v[82:89], v[34:49], v194, v194 op_sel_hi:[0,0,0]
	s_waitcnt lgkmcnt(0)
	s_barrier
	s_waitcnt lgkmcnt(2)
	v_mfma_scale_f32_32x32x64_f8f6f4 v[18:33], v[246:253], v[74:81], v[18:33], v194, v194 op_sel_hi:[0,0,0]
	global_load_dwordx4 v[158:161], v176, s[18:19]
	global_load_dwordx4 v[162:165], v178, s[16:17]
	v_add_u32_e32 v176, 0x2000, v176
	v_add_u32_e32 v178, 0x20000, v178
	s_waitcnt lgkmcnt(0)
	v_mfma_scale_f32_32x32x64_f8f6f4 v[2:17], v[246:253], v[66:73], v[2:17], v194, v194 op_sel_hi:[0,0,0]
	v_max_f32_e32 v0, v98, v99
	v_max3_f32 v0, v0, v100, v101
	v_max3_f32 v0, v0, v102, v103
	v_max3_f32 v0, v0, v104, v105
	v_max3_f32 v0, v0, v106, v107
	v_max3_f32 v0, v0, v108, v109
	v_max3_f32 v0, v0, v110, v111
	v_max3_f32 v0, v0, v112, v113
	v_max_f32_e32 v177, v177, v0
	v_mov_b32_e32 v0, v177
	s_nop 1
	v_permlane32_swap_b32_e32 v177, v0
	v_max_f32_e32 v177, v177, v0
	v_cmp_ge_f32_e32 vcc, s90, v177
	s_cmp_eq_u64 vcc, exec
	s_cbranch_scc0 .Lmla_q0_newmax
; __device__ __forceinline__ void finishSM9(f32x16& p0, f32x16& p1, float alpha, float& l_reg, v8i32& p8) {
; #pragma unroll
;   for (int r = 0; r < 16; ++r) { p0[r] = __builtin_amdgcn_exp2f(p0[r]); p1[r] = __builtin_amdgcn_exp2f(p1[r]); }
;   float ps = 0;
; #pragma unroll
;   for (int r = 0; r < 16; ++r) ps += p0[r];
; #pragma unroll
;   for (int r = 0; r < 16; ++r) ps += p1[r];
;   { auto rr = __builtin_amdgcn_permlane32_swap(__float_as_uint(ps), __float_as_uint(ps), false, false);
;     ps = __uint_as_float(rr[0]) + __uint_as_float(rr[1]); }
;   l_reg = l_reg * alpha + ps;
; #pragma unroll
;   for (int g = 0; g < 4; ++g) {
;     int w = __builtin_amdgcn_cvt_pk_fp8_f32(p0[4 * g], p0[4 * g + 1], 0, false); p8[g] = __builtin_amdgcn_cvt_pk_fp8_f32(p0[4 * g + 2], p0[4 * g + 3], w, true);
;     int u = __builtin_amdgcn_cvt_pk_fp8_f32(p1[4 * g], p1[4 * g + 1], 0, false); p8[4 + g] = __builtin_amdgcn_cvt_pk_fp8_f32(p1[4 * g + 2], p1[4 * g + 3], u, true); }
; }
; __device__ __forceinline__ void pv8(f32x16* o, const char* Vt, const v8i32 p8, int r32, int hi) {
;   const int sw = (r32 >> 2) & 3, a0 = r32 * 64 + (((hi * 2) ^ sw) << 4), a1 = r32 * 64 + (((hi * 2 + 1) ^ sw) << 4);
; #pragma unroll
;   for (int d0 = 0; d0 < 4; ++d0) {
;     const v8i32 vf = cat8(*reinterpret_cast<const v4i32*>(Vt + d0 * 2048 + a0), *reinterpret_cast<const v4i32*>(Vt + d0 * 2048 + a1));
;     o[d0] = __builtin_amdgcn_mfma_scale_f32_32x32x64_f8f6f4(p8, vf, o[d0], 0, 0, 0, 127, 0, 127); }
; }
; __device__ __forceinline__ void qkt9(f32x16& p0, f32x16& p1, const char* Kn, const char* Kr, const v8i32* qf, const float init, int r32, int hi) {
; #pragma unroll
;   for (int r = 0; r < 16; ++r) { p0[r] = init; p1[r] = init; }
; #pragma unroll
;   for (int s = 0; s < 2; ++s) { const int c0 = s * 4 + hi * 2;
;     const v8i32 a0 = cat8(*reinterpret_cast<const v4i32*>(Kn + KN8SW(r32, c0)), *reinterpret_cast<const v4i32*>(Kn + KN8SW(r32, c0 + 1)));
;     const v8i32 a1 = cat8(*reinterpret_cast<const v4i32*>(Kn + 4096 + KN8SW(r32, c0)), *reinterpret_cast<const v4i32*>(Kn + 4096 + KN8SW(r32, c0 + 1)));
;     p0 = __builtin_amdgcn_mfma_scale_f32_32x32x64_f8f6f4(a0, qf[s], p0, 0, 0, 0, 127, 0, 124);
;     p1 = __builtin_amdgcn_mfma_scale_f32_32x32x64_f8f6f4(a1, qf[s], p1, 0, 0, 0, 127, 0, 124); }
;   { const int c0 = hi * 2;
.Lmla_q0_cont:
	ds_read_b128 v[82:85], v215 offset:51200
	ds_read_b128 v[86:89], v216 offset:51200
	ds_read_b128 v[222:225], v215 offset:55296
	ds_read_b128 v[226:229], v216 offset:55296
	v_exp_f32_e32 v0, v114
	v_exp_f32_e32 v177, v115
	v_exp_f32_e32 v179, v116
	v_exp_f32_e32 v254, v117
	v_add_f32_e32 v219, v0, v177
	v_cvt_pk_fp8_f32 v246, v0, v177
	v_add_f32_e32 v219, v179, v219
	v_add_f32_e32 v219, v254, v219
	v_cvt_pk_fp8_f32 v246, v179, v254 op_sel:[0,0,1]
	s_waitcnt lgkmcnt(2)
	v_mfma_scale_f32_32x32x64_f8f6f4 v[82:97], v[82:89], v[146:153], v[230:245], v194, v193 op_sel_hi:[0,0,0]
	v_exp_f32_e32 v0, v118
	v_exp_f32_e32 v177, v119
	v_exp_f32_e32 v179, v120
	v_exp_f32_e32 v254, v121
	v_add_f32_e32 v219, v0, v219
	v_add_f32_e32 v219, v177, v219
	v_cvt_pk_fp8_f32 v247, v0, v177
	v_add_f32_e32 v219, v179, v219
	v_add_f32_e32 v219, v254, v219
	v_cvt_pk_fp8_f32 v247, v179, v254 op_sel:[0,0,1]
	ds_read_b128 v[114:117], v213 offset:51200
	ds_read_b128 v[118:121], v214 offset:51200
	s_waitcnt lgkmcnt(2)
	v_mfma_scale_f32_32x32x64_f8f6f4 v[66:81], v[222:229], v[146:153], v[230:245], v194, v193 op_sel_hi:[0,0,0]
	ds_read_b128 v[222:225], v213 offset:55296
	ds_read_b128 v[226:229], v214 offset:55296
	v_exp_f32_e32 v0, v122
	v_exp_f32_e32 v177, v123
	v_exp_f32_e32 v179, v124
	v_exp_f32_e32 v254, v125
	v_add_f32_e32 v219, v0, v219
	v_add_f32_e32 v219, v177, v219
	v_cvt_pk_fp8_f32 v248, v0, v177
	v_add_f32_e32 v219, v179, v219
	v_add_f32_e32 v219, v254, v219
	v_cvt_pk_fp8_f32 v248, v179, v254 op_sel:[0,0,1]
	v_exp_f32_e32 v0, v126
	v_exp_f32_e32 v177, v127
	v_exp_f32_e32 v179, v128
	v_exp_f32_e32 v254, v129
	v_add_f32_e32 v219, v0, v219
	v_add_f32_e32 v219, v177, v219
	v_cvt_pk_fp8_f32 v249, v0, v177
	v_add_f32_e32 v219, v179, v219
	v_add_f32_e32 v219, v254, v219
	v_cvt_pk_fp8_f32 v249, v179, v254 op_sel:[0,0,1]
	ds_read_b128 v[122:125], v185 offset:59392
	ds_read_b128 v[126:129], v186 offset:59392
	s_waitcnt lgkmcnt(4)
	v_mfma_scale_f32_32x32x64_f8f6f4 v[82:97], v[114:121], v[138:145], v[82:97], v194, v193 op_sel_hi:[0,0,0]
	v_exp_f32_e32 v0, v98
	v_exp_f32_e32 v177, v99
	v_exp_f32_e32 v179, v100
	v_exp_f32_e32 v254, v101
	v_add_f32_e32 v219, v0, v219
	v_add_f32_e32 v219, v177, v219
	v_cvt_pk_fp8_f32 v250, v0, v177
	v_add_f32_e32 v219, v179, v219
	v_add_f32_e32 v219, v254, v219
	v_cvt_pk_fp8_f32 v250, v179, v254 op_sel:[0,0,1]
	s_waitcnt lgkmcnt(2)
	v_mfma_scale_f32_32x32x64_f8f6f4 v[66:81], v[222:229], v[138:145], v[66:81], v194, v193 op_sel_hi:[0,0,0]
	ds_read_b128 v[222:225], v185 offset:61440
	ds_read_b128 v[226:229], v186 offset:61440
	v_exp_f32_e32 v0, v102
	v_exp_f32_e32 v177, v103
	v_exp_f32_e32 v179, v104
	v_exp_f32_e32 v254, v105
	v_add_f32_e32 v219, v0, v219
	v_add_f32_e32 v219, v177, v219
	v_cvt_pk_fp8_f32 v251, v0, v177
	v_add_f32_e32 v219, v179, v219
	v_add_f32_e32 v219, v254, v219
	v_cvt_pk_fp8_f32 v251, v179, v254 op_sel:[0,0,1]
	v_exp_f32_e32 v0, v106
	v_exp_f32_e32 v177, v107
	v_exp_f32_e32 v179, v108
	v_exp_f32_e32 v254, v109
	v_add_f32_e32 v219, v0, v219
	v_add_f32_e32 v219, v177, v219
	v_cvt_pk_fp8_f32 v252, v0, v177
	v_add_f32_e32 v219, v179, v219
	v_add_f32_e32 v219, v254, v219
	v_cvt_pk_fp8_f32 v252, v179, v254 op_sel:[0,0,1]
	s_waitcnt lgkmcnt(2)
	v_mfma_scale_f32_32x32x64_f8f6f4 v[82:97], v[122:129], v[130:137], v[82:97], v194, v193 op_sel_hi:[0,0,0]
	v_exp_f32_e32 v0, v110
	v_exp_f32_e32 v177, v111
	v_exp_f32_e32 v179, v112
	v_exp_f32_e32 v254, v113
	v_add_f32_e32 v219, v0, v219
	v_add_f32_e32 v219, v177, v219
	v_cvt_pk_fp8_f32 v253, v0, v177
	v_add_f32_e32 v219, v179, v219
	v_add_f32_e32 v219, v254, v219
	v_cvt_pk_fp8_f32 v253, v179, v254 op_sel:[0,0,1]
	ds_read_b128 v[122:125], v185 offset:8192
	ds_read_b128 v[126:129], v186 offset:8192
	ds_read_b128 v[114:117], v185 offset:10240
	ds_read_b128 v[118:121], v186 offset:10240
	ds_read_b128 v[106:109], v185 offset:12288
	ds_read_b128 v[110:113], v186 offset:12288
	ds_read_b128 v[98:101], v185 offset:14336
	ds_read_b128 v[102:105], v186 offset:14336
	s_waitcnt lgkmcnt(8)
	v_mfma_scale_f32_32x32x64_f8f6f4 v[66:81], v[222:229], v[130:137], v[66:81], v194, v193 op_sel_hi:[0,0,0]
	v_mov_b32_e32 v0, v219
	s_nop 1
	v_permlane32_swap_b32_e32 v219, v0
	v_add_f32_e32 v219, v219, v0
	v_add_f32_e32 v209, v209, v219
	v_max_f32_e32 v177, v82, v83
	v_max3_f32 v177, v177, v84, v85
	v_max3_f32 v177, v177, v86, v87
	v_max3_f32 v177, v177, v88, v89
	v_max3_f32 v177, v177, v90, v91
	v_max3_f32 v177, v177, v92, v93
	v_max3_f32 v177, v177, v94, v95
	v_max3_f32 v177, v177, v96, v97
	s_waitcnt lgkmcnt(6)
	v_mfma_scale_f32_32x32x64_f8f6f4 v[50:65], v[246:253], v[122:129], v[50:65], v194, v194 op_sel_hi:[0,0,0]
	s_waitcnt vmcnt(0)
	ds_write_b128 v210, v[158:161]
	ds_write_b128 v211, v[162:165] offset:16384
	s_waitcnt lgkmcnt(6)
	v_mfma_scale_f32_32x32x64_f8f6f4 v[34:49], v[246:253], v[114:121], v[34:49], v194, v194 op_sel_hi:[0,0,0]
	s_waitcnt lgkmcnt(0)
	s_barrier
	s_waitcnt lgkmcnt(2)
	v_mfma_scale_f32_32x32x64_f8f6f4 v[18:33], v[246:253], v[106:113], v[18:33], v194, v194 op_sel_hi:[0,0,0]
	s_waitcnt lgkmcnt(0)
	v_mfma_scale_f32_32x32x64_f8f6f4 v[2:17], v[246:253], v[98:105], v[2:17], v194, v194 op_sel_hi:[0,0,0]
	v_max_f32_e32 v0, v66, v67
	v_max3_f32 v0, v0, v68, v69
	v_max3_f32 v0, v0, v70, v71
	v_max3_f32 v0, v0, v72, v73
	v_max3_f32 v0, v0, v74, v75
	v_max3_f32 v0, v0, v76, v77
	v_max3_f32 v0, v0, v78, v79
	v_max3_f32 v0, v0, v80, v81
	v_max_f32_e32 v177, v177, v0
	v_mov_b32_e32 v0, v177
	s_nop 1
	v_permlane32_swap_b32_e32 v177, v0
	v_max_f32_e32 v177, v177, v0
	v_cmp_ge_f32_e32 vcc, s90, v177
	s_cmp_eq_u64 vcc, exec
	s_cbranch_scc0 .Lmla_q1_newmax
